# GEMM K-loops: priority raise moved in front of the opening barrier, priority drop behind the closing barrier, redundant post-barrier lgkmcnt(0) removed
# speedup vs baseline: 1.0022x; 1.0022x over previous
; #define PG8_STAGE(bufoff, gbase, voff) do { _Pragma("unroll") for (int _i = 0; _i < 2; ++_i) \
;         __builtin_amdgcn_global_load_lds((const unsigned*)((const char*)(gbase) + (voff)[_i]), (PG8_LAS unsigned*)(lds + (bufoff) + ldsw + _i * 8192), 16, 0, 0); } while (0)
; #define PG8_LDA(dst, b, h) do { _Pragma("unroll") for (int m = 0; m < 4; ++m) _Pragma("unroll") for (int k = 0; k < 2; ++k) dst[m][k] = *(const PG8_LAS bf16x8*)(lds + PG8_SA(b, h) + aoff + m * 2048 + k * 1024); } while (0)
; #define PG8_LDB(dst, b, h) do { _Pragma("unroll") for (int n = 0; n < 2; ++n) _Pragma("unroll") for (int k = 0; k < 2; ++k) dst[n][k] = *(const PG8_LAS bf16x8*)(lds + PG8_SB(b, h) + boff + n * 2048 + k * 1024); } while (0)
; #define PG8_MMA(ai, bj, At, Bt) do { __builtin_amdgcn_s_setprio(1); _Pragma("unroll") for (int m = 0; m < 4; ++m) _Pragma("unroll") for (int n = 0; n < 2; ++n) _Pragma("unroll") for (int k = 0; k < 2; ++k) \
;         acc[ai][bj][m][n] = __builtin_amdgcn_mfma_f32_16x16x32_bf16(Bt[n][k], At[m][k], acc[ai][bj][m][n], 0, 0, 0); __builtin_amdgcn_s_setprio(0); } while (0)
; #define PG8_WAIT_V(n) asm volatile("s_waitcnt vmcnt(" #n ")" ::: "memory")
; #define PG8_WAIT_L(n) asm volatile("s_waitcnt lgkmcnt(" #n ")" ::: "memory")
; template <class Epi, class Sched, bool ALIGN_EPI = false, bool SP2 = false>
; __device__ __forceinline__ void gemm_phase(PG8_LAS unsigned char* lds, const Gemm g, const Sched& S, const Epi& E, const int wave_) {
;     ...
;             const bool last = (t == nt - 2);
;             const char* a1 = cA + (size_t)(t + 1) * kstep;
;             const char* a2 = last ? nA : cA + (size_t)(t + 2) * kstep; const char* b2 = last ? nB : cB + (size_t)(t + 2) * kstep;
;             const char* a3 = a2 + kstep; const char* b3 = b2 + kstep;
;             if (last && has_next) S.a_ready(nxt);
;             if constexpr (SP2) {
;             PG8_LDB(B0, 0, 0); PG8_LDB(B1, 0, 1); PG8_SCHED; PG8_LDA(At, 0, 0); PG8_STAGE(PG8_SA(1, 1), a1 + hstep, voffA);
;             PG8_WAIT_V(8); PG8_WAIT_L(0); PG8_BAR; PG8_MMA(0, 0, At, B0); PG8_MMA(0, 1, At, B1); PG8_BAR; PG8_SCHED;
;             PG8_LDA(At, 0, 1); PG8_STAGE(PG8_SB(0, 0), b2, voffB); PG8_STAGE(PG8_SB(0, 1), b2 + hstep, voffB); PG8_STAGE(PG8_SA(0, 0), a2, voffA);
;             PG8_WAIT_V(8); PG8_WAIT_L(0); PG8_BAR; PG8_MMA(1, 0, At, B0); PG8_MMA(1, 1, At, B1); PG8_BAR; PG8_SCHED;
.LBB0_129:
	s_waitcnt lgkmcnt(0)
	ds_read_b128 v[158:161], v202
	ds_read_b128 v[162:165], v202 offset:1024
	ds_read_b128 v[166:169], v202 offset:2048
	ds_read_b128 v[170:173], v202 offset:3072
	ds_read_b128 v[174:177], v205
	ds_read_b128 v[178:181], v205 offset:1024
	ds_read_b128 v[182:185], v205 offset:2048
	ds_read_b128 v[186:189], v205 offset:3072
	s_add_u32 s23, s46, 0xfff80080
	s_addc_u32 s24, s47, -1
	s_cmp_eq_u32 s22, 28
	s_cselect_b32 s51, s19, s24
	s_cselect_b32 s50, s39, s23
	s_cselect_b32 s49, s37, s97
	s_cselect_b32 s48, vcc_lo, vcc_hi
	v_lshl_add_u64 v[238:239], s[46:47], 0, v[148:149]
	s_add_i32 m0, s53, 0xc000
	ds_read_b128 v[206:209], v203
	ds_read_b128 v[210:213], v203 offset:1024
	ds_read_b128 v[214:217], v203 offset:2048
	ds_read_b128 v[218:221], v203 offset:3072
	ds_read_b128 v[222:225], v203 offset:4096
	ds_read_b128 v[226:229], v203 offset:5120
	ds_read_b128 v[230:233], v203 offset:6144
	ds_read_b128 v[234:237], v203 offset:7168
	global_load_lds_dwordx4 v[238:239], off
	v_lshl_add_u64 v[238:239], s[46:47], 0, v[150:151]
	s_add_i32 m0, s53, 0xe000
	s_nop 0
	global_load_lds_dwordx4 v[238:239], off
	s_waitcnt vmcnt(8)
	s_waitcnt lgkmcnt(0)
	s_setprio 1
	s_barrier
	v_mfma_f32_16x16x32_bf16 v[124:127], v[158:161], v[206:209], v[124:127]
	v_mfma_f32_16x16x32_bf16 v[116:119], v[166:169], v[206:209], v[116:119]
	v_mfma_f32_16x16x32_bf16 v[108:111], v[158:161], v[214:217], v[108:111]
	v_mfma_f32_16x16x32_bf16 v[100:103], v[166:169], v[214:217], v[100:103]
	v_mfma_f32_16x16x32_bf16 v[92:95], v[158:161], v[222:225], v[92:95]
	v_mfma_f32_16x16x32_bf16 v[84:87], v[166:169], v[222:225], v[84:87]
	v_mfma_f32_16x16x32_bf16 v[76:79], v[158:161], v[230:233], v[76:79]
	v_mfma_f32_16x16x32_bf16 v[68:71], v[166:169], v[230:233], v[68:71]
	v_mfma_f32_16x16x32_bf16 v[124:127], v[162:165], v[210:213], v[124:127]
	v_mfma_f32_16x16x32_bf16 v[116:119], v[170:173], v[210:213], v[116:119]
	v_mfma_f32_16x16x32_bf16 v[108:111], v[162:165], v[218:221], v[108:111]
	v_mfma_f32_16x16x32_bf16 v[100:103], v[170:173], v[218:221], v[100:103]
	v_mfma_f32_16x16x32_bf16 v[92:95], v[162:165], v[226:229], v[92:95]
	v_mfma_f32_16x16x32_bf16 v[84:87], v[170:173], v[226:229], v[84:87]
	v_mfma_f32_16x16x32_bf16 v[76:79], v[162:165], v[234:237], v[76:79]
	v_mfma_f32_16x16x32_bf16 v[68:71], v[170:173], v[234:237], v[68:71]
	s_setprio 0
	s_setprio 1
	v_mfma_f32_16x16x32_bf16 v[120:123], v[174:177], v[206:209], v[120:123]
	v_mfma_f32_16x16x32_bf16 v[112:115], v[182:185], v[206:209], v[112:115]
	v_mfma_f32_16x16x32_bf16 v[104:107], v[174:177], v[214:217], v[104:107]
	v_mfma_f32_16x16x32_bf16 v[96:99], v[182:185], v[214:217], v[96:99]
	v_mfma_f32_16x16x32_bf16 v[88:91], v[174:177], v[222:225], v[88:91]
	v_mfma_f32_16x16x32_bf16 v[80:83], v[182:185], v[222:225], v[80:83]
	v_mfma_f32_16x16x32_bf16 v[72:75], v[174:177], v[230:233], v[72:75]
	v_mfma_f32_16x16x32_bf16 v[64:67], v[182:185], v[230:233], v[64:67]
	v_mfma_f32_16x16x32_bf16 v[120:123], v[178:181], v[210:213], v[120:123]
	v_mfma_f32_16x16x32_bf16 v[112:115], v[186:189], v[210:213], v[112:115]
	v_mfma_f32_16x16x32_bf16 v[104:107], v[178:181], v[218:221], v[104:107]
	v_mfma_f32_16x16x32_bf16 v[96:99], v[186:189], v[218:221], v[96:99]
	v_mfma_f32_16x16x32_bf16 v[88:91], v[178:181], v[226:229], v[88:91]
	v_mfma_f32_16x16x32_bf16 v[80:83], v[186:189], v[226:229], v[80:83]
	v_mfma_f32_16x16x32_bf16 v[72:75], v[178:181], v[234:237], v[72:75]
	v_mfma_f32_16x16x32_bf16 v[64:67], v[186:189], v[234:237], v[64:67]
	s_barrier
	s_setprio 0
	s_add_i32 s23, s67, s52
	v_lshl_add_u64 v[238:239], s[48:49], 0, v[130:131]
	s_mov_b32 m0, s23
	ds_read_b128 v[206:209], v203 offset:16384
	ds_read_b128 v[210:213], v203 offset:17408
	ds_read_b128 v[214:217], v203 offset:18432
	ds_read_b128 v[218:221], v203 offset:19456
	ds_read_b128 v[222:225], v203 offset:20480
	ds_read_b128 v[226:229], v203 offset:21504
	ds_read_b128 v[230:233], v203 offset:22528
	ds_read_b128 v[234:237], v203 offset:23552
	global_load_lds_dwordx4 v[238:239], off
	s_add_i32 m0, s23, 0x2000
	s_add_u32 s24, s48, 0x80000
	v_lshl_add_u64 v[240:241], s[48:49], 0, v[134:135]
	s_addc_u32 s25, s49, 0
	s_add_i32 s23, s71, s52
	global_load_lds_dwordx4 v[240:241], off
	v_lshl_add_u64 v[242:243], s[24:25], 0, v[130:131]
	s_mov_b32 m0, s23
	v_lshl_add_u64 v[244:245], s[50:51], 0, v[132:133]
	global_load_lds_dwordx4 v[242:243], off
	v_lshl_add_u64 v[242:243], s[24:25], 0, v[134:135]
	s_add_i32 m0, s23, 0x2000
	s_nop 0
	global_load_lds_dwordx4 v[242:243], off
	v_lshl_add_u64 v[242:243], s[50:51], 0, v[128:129]
	s_mov_b32 m0, s53
	s_nop 0
	global_load_lds_dwordx4 v[242:243], off
	s_mov_b32 m0, s54
	s_nop 0
	global_load_lds_dwordx4 v[244:245], off
	s_waitcnt vmcnt(8)
	s_waitcnt lgkmcnt(0)
	s_setprio 1
	s_barrier
; #define PG8_STAGE(bufoff, gbase, voff) do { _Pragma("unroll") for (int _i = 0; _i < 2; ++_i) \
;         __builtin_amdgcn_global_load_lds((const unsigned*)((const char*)(gbase) + (voff)[_i]), (PG8_LAS unsigned*)(lds + (bufoff) + ldsw + _i * 8192), 16, 0, 0); } while (0)
; #define PG8_LDA(dst, b, h) do { _Pragma("unroll") for (int m = 0; m < 4; ++m) _Pragma("unroll") for (int k = 0; k < 2; ++k) dst[m][k] = *(const PG8_LAS bf16x8*)(lds + PG8_SA(b, h) + aoff + m * 2048 + k * 1024); } while (0)
; #define PG8_LDB(dst, b, h) do { _Pragma("unroll") for (int n = 0; n < 2; ++n) _Pragma("unroll") for (int k = 0; k < 2; ++k) dst[n][k] = *(const PG8_LAS bf16x8*)(lds + PG8_SB(b, h) + boff + n * 2048 + k * 1024); } while (0)
; #define PG8_MMA(ai, bj, At, Bt) do { __builtin_amdgcn_s_setprio(1); _Pragma("unroll") for (int m = 0; m < 4; ++m) _Pragma("unroll") for (int n = 0; n < 2; ++n) _Pragma("unroll") for (int k = 0; k < 2; ++k) \
;         acc[ai][bj][m][n] = __builtin_amdgcn_mfma_f32_16x16x32_bf16(Bt[n][k], At[m][k], acc[ai][bj][m][n], 0, 0, 0); __builtin_amdgcn_s_setprio(0); } while (0)
; #define PG8_WAIT_V(n) asm volatile("s_waitcnt vmcnt(" #n ")" ::: "memory")
; #define PG8_WAIT_L(n) asm volatile("s_waitcnt lgkmcnt(" #n ")" ::: "memory")
; #define PG8_BAR __builtin_amdgcn_s_barrier()
; #define PG8_SCHED __builtin_amdgcn_sched_barrier(0)
; template <class Epi, class Sched, bool ALIGN_EPI = false, bool SP2 = false>
; __device__ __forceinline__ void gemm_phase(PG8_LAS unsigned char* lds, const Gemm g, const Sched& S, const Epi& E, const int wave_) {
;     ...
;             PG8_WAIT_V(8); PG8_WAIT_L(0); PG8_BAR; PG8_MMA(1, 0, At, B0); PG8_MMA(1, 1, At, B1); PG8_BAR; PG8_SCHED;
;             PG8_LDB(B0, 1, 0); PG8_LDB(B1, 1, 1); PG8_SCHED; PG8_LDA(At, 1, 0); PG8_STAGE(PG8_SA(0, 1), a2 + hstep, voffA);
;             PG8_WAIT_V(8); PG8_WAIT_L(0); PG8_BAR; PG8_MMA(0, 0, At, B0); PG8_MMA(0, 1, At, B1); PG8_BAR; PG8_SCHED;
	v_mfma_f32_16x16x32_bf16 v[60:63], v[158:161], v[206:209], v[60:63]
	v_mfma_f32_16x16x32_bf16 v[52:55], v[166:169], v[206:209], v[52:55]
	v_mfma_f32_16x16x32_bf16 v[44:47], v[158:161], v[214:217], v[44:47]
	v_mfma_f32_16x16x32_bf16 v[36:39], v[166:169], v[214:217], v[36:39]
	v_mfma_f32_16x16x32_bf16 v[28:31], v[158:161], v[222:225], v[28:31]
	v_mfma_f32_16x16x32_bf16 v[20:23], v[166:169], v[222:225], v[20:23]
	v_mfma_f32_16x16x32_bf16 v[12:15], v[158:161], v[230:233], v[12:15]
	v_mfma_f32_16x16x32_bf16 v[4:7], v[166:169], v[230:233], v[4:7]
	v_mfma_f32_16x16x32_bf16 v[60:63], v[162:165], v[210:213], v[60:63]
	v_mfma_f32_16x16x32_bf16 v[52:55], v[170:173], v[210:213], v[52:55]
	v_mfma_f32_16x16x32_bf16 v[44:47], v[162:165], v[218:221], v[44:47]
	v_mfma_f32_16x16x32_bf16 v[36:39], v[170:173], v[218:221], v[36:39]
	v_mfma_f32_16x16x32_bf16 v[28:31], v[162:165], v[226:229], v[28:31]
	v_mfma_f32_16x16x32_bf16 v[20:23], v[170:173], v[226:229], v[20:23]
	v_mfma_f32_16x16x32_bf16 v[12:15], v[162:165], v[234:237], v[12:15]
	v_mfma_f32_16x16x32_bf16 v[4:7], v[170:173], v[234:237], v[4:7]
	s_setprio 0
	s_setprio 1
	v_mfma_f32_16x16x32_bf16 v[56:59], v[174:177], v[206:209], v[56:59]
	v_mfma_f32_16x16x32_bf16 v[48:51], v[182:185], v[206:209], v[48:51]
	v_mfma_f32_16x16x32_bf16 v[40:43], v[174:177], v[214:217], v[40:43]
	v_mfma_f32_16x16x32_bf16 v[32:35], v[182:185], v[214:217], v[32:35]
	v_mfma_f32_16x16x32_bf16 v[24:27], v[174:177], v[222:225], v[24:27]
	v_mfma_f32_16x16x32_bf16 v[16:19], v[182:185], v[222:225], v[16:19]
	v_mfma_f32_16x16x32_bf16 v[8:11], v[174:177], v[230:233], v[8:11]
	v_mfma_f32_16x16x32_bf16 v[0:3], v[182:185], v[230:233], v[0:3]
	v_mfma_f32_16x16x32_bf16 v[56:59], v[178:181], v[210:213], v[56:59]
	v_mfma_f32_16x16x32_bf16 v[48:51], v[186:189], v[210:213], v[48:51]
	v_mfma_f32_16x16x32_bf16 v[40:43], v[178:181], v[218:221], v[40:43]
	v_mfma_f32_16x16x32_bf16 v[32:35], v[186:189], v[218:221], v[32:35]
	v_mfma_f32_16x16x32_bf16 v[24:27], v[178:181], v[226:229], v[24:27]
	v_mfma_f32_16x16x32_bf16 v[16:19], v[186:189], v[226:229], v[16:19]
	v_mfma_f32_16x16x32_bf16 v[8:11], v[178:181], v[234:237], v[8:11]
	v_mfma_f32_16x16x32_bf16 v[0:3], v[186:189], v[234:237], v[0:3]
	s_barrier
	s_setprio 0
	s_add_i32 s23, 0, 0x18000
	s_add_i32 s86, 0, 0x1c000
	v_add_u32_e32 v170, s23, v191
	v_add_u32_e32 v186, s86, v191
	ds_read_b128 v[158:161], v170
	ds_read_b128 v[162:165], v170 offset:1024
	ds_read_b128 v[166:169], v170 offset:2048
	ds_read_b128 v[170:173], v170 offset:3072
	ds_read_b128 v[174:177], v186
	ds_read_b128 v[178:181], v186 offset:1024
	ds_read_b128 v[182:185], v186 offset:2048
	ds_read_b128 v[186:189], v186 offset:3072
	s_add_u32 s24, s50, 0x80000
	s_addc_u32 s25, s51, 0
	s_mov_b32 m0, s55
	v_lshl_add_u64 v[246:247], s[24:25], 0, v[128:129]
	ds_read_b128 v[206:209], v203 offset:32768
	ds_read_b128 v[210:213], v203 offset:33792
	ds_read_b128 v[214:217], v203 offset:34816
	ds_read_b128 v[218:221], v203 offset:35840
	ds_read_b128 v[222:225], v203 offset:36864
	ds_read_b128 v[226:229], v203 offset:37888
	ds_read_b128 v[230:233], v203 offset:38912
	ds_read_b128 v[234:237], v203 offset:39936
	global_load_lds_dwordx4 v[246:247], off
	v_lshl_add_u64 v[246:247], s[24:25], 0, v[132:133]
	s_mov_b32 m0, s56
	s_nop 0
	global_load_lds_dwordx4 v[246:247], off
	s_waitcnt vmcnt(8)
	s_waitcnt lgkmcnt(0)
	s_setprio 1
	s_barrier
	v_mfma_f32_16x16x32_bf16 v[124:127], v[158:161], v[206:209], v[124:127]
	v_mfma_f32_16x16x32_bf16 v[116:119], v[166:169], v[206:209], v[116:119]
	v_mfma_f32_16x16x32_bf16 v[108:111], v[158:161], v[214:217], v[108:111]
	v_mfma_f32_16x16x32_bf16 v[100:103], v[166:169], v[214:217], v[100:103]
	v_mfma_f32_16x16x32_bf16 v[92:95], v[158:161], v[222:225], v[92:95]
	v_mfma_f32_16x16x32_bf16 v[84:87], v[166:169], v[222:225], v[84:87]
	v_mfma_f32_16x16x32_bf16 v[76:79], v[158:161], v[230:233], v[76:79]
	v_mfma_f32_16x16x32_bf16 v[68:71], v[166:169], v[230:233], v[68:71]
	v_mfma_f32_16x16x32_bf16 v[124:127], v[162:165], v[210:213], v[124:127]
	v_mfma_f32_16x16x32_bf16 v[116:119], v[170:173], v[210:213], v[116:119]
	v_mfma_f32_16x16x32_bf16 v[108:111], v[162:165], v[218:221], v[108:111]
	v_mfma_f32_16x16x32_bf16 v[100:103], v[170:173], v[218:221], v[100:103]
	v_mfma_f32_16x16x32_bf16 v[92:95], v[162:165], v[226:229], v[92:95]
	v_mfma_f32_16x16x32_bf16 v[84:87], v[170:173], v[226:229], v[84:87]
	v_mfma_f32_16x16x32_bf16 v[76:79], v[162:165], v[234:237], v[76:79]
	v_mfma_f32_16x16x32_bf16 v[68:71], v[170:173], v[234:237], v[68:71]
	s_setprio 0
	s_setprio 1
	v_mfma_f32_16x16x32_bf16 v[120:123], v[174:177], v[206:209], v[120:123]
	v_mfma_f32_16x16x32_bf16 v[112:115], v[182:185], v[206:209], v[112:115]
	v_mfma_f32_16x16x32_bf16 v[104:107], v[174:177], v[214:217], v[104:107]
	v_mfma_f32_16x16x32_bf16 v[96:99], v[182:185], v[214:217], v[96:99]
	v_mfma_f32_16x16x32_bf16 v[88:91], v[174:177], v[222:225], v[88:91]
	v_mfma_f32_16x16x32_bf16 v[80:83], v[182:185], v[222:225], v[80:83]
	v_mfma_f32_16x16x32_bf16 v[72:75], v[174:177], v[230:233], v[72:75]
	v_mfma_f32_16x16x32_bf16 v[64:67], v[182:185], v[230:233], v[64:67]
	v_mfma_f32_16x16x32_bf16 v[120:123], v[178:181], v[210:213], v[120:123]
	v_mfma_f32_16x16x32_bf16 v[112:115], v[186:189], v[210:213], v[112:115]
	v_mfma_f32_16x16x32_bf16 v[104:107], v[178:181], v[218:221], v[104:107]
	v_mfma_f32_16x16x32_bf16 v[96:99], v[186:189], v[218:221], v[96:99]
	v_mfma_f32_16x16x32_bf16 v[88:91], v[178:181], v[226:229], v[88:91]
	v_mfma_f32_16x16x32_bf16 v[80:83], v[186:189], v[226:229], v[80:83]
	v_mfma_f32_16x16x32_bf16 v[72:75], v[178:181], v[234:237], v[72:75]
	v_mfma_f32_16x16x32_bf16 v[64:67], v[186:189], v[234:237], v[64:67]
	s_barrier
; #define PG8_STAGE(bufoff, gbase, voff) do { _Pragma("unroll") for (int _i = 0; _i < 2; ++_i) \
;         __builtin_amdgcn_global_load_lds((const unsigned*)((const char*)(gbase) + (voff)[_i]), (PG8_LAS unsigned*)(lds + (bufoff) + ldsw + _i * 8192), 16, 0, 0); } while (0)
; #define PG8_LDA(dst, b, h) do { _Pragma("unroll") for (int m = 0; m < 4; ++m) _Pragma("unroll") for (int k = 0; k < 2; ++k) dst[m][k] = *(const PG8_LAS bf16x8*)(lds + PG8_SA(b, h) + aoff + m * 2048 + k * 1024); } while (0)
; #define PG8_MMA(ai, bj, At, Bt) do { __builtin_amdgcn_s_setprio(1); _Pragma("unroll") for (int m = 0; m < 4; ++m) _Pragma("unroll") for (int n = 0; n < 2; ++n) _Pragma("unroll") for (int k = 0; k < 2; ++k) \
;         acc[ai][bj][m][n] = __builtin_amdgcn_mfma_f32_16x16x32_bf16(Bt[n][k], At[m][k], acc[ai][bj][m][n], 0, 0, 0); __builtin_amdgcn_s_setprio(0); } while (0)
; #define PG8_WAIT_V(n) asm volatile("s_waitcnt vmcnt(" #n ")" ::: "memory")
; #define PG8_WAIT_L(n) asm volatile("s_waitcnt lgkmcnt(" #n ")" ::: "memory")
; #define PG8_BAR __builtin_amdgcn_s_barrier()
; #define PG8_SCHED __builtin_amdgcn_sched_barrier(0)
; template <class Epi, class Sched, bool ALIGN_EPI = false, bool SP2 = false>
; __device__ __forceinline__ void gemm_phase(PG8_LAS unsigned char* lds, const Gemm g, const Sched& S, const Epi& E, const int wave_) {
;     ...
;         for (int t = 0; t < nt; t += 2) {
;     ...
;             PG8_LDA(At, 1, 1); PG8_STAGE(PG8_SB(1, 0), b3, voffB); PG8_STAGE(PG8_SB(1, 1), b3 + hstep, voffB); PG8_STAGE(PG8_SA(1, 0), a3, voffA);
;             PG8_WAIT_V(8); PG8_WAIT_L(0); PG8_BAR; PG8_MMA(1, 0, At, B0); PG8_MMA(1, 1, At, B1); PG8_BAR; PG8_SCHED;
	s_setprio 0
	s_add_i32 s23, s23, s52
	v_lshl_add_u64 v[238:239], v[238:239], 0, s[34:35]
	s_mov_b32 m0, s23
	ds_read_b128 v[206:209], v203 offset:49152
	ds_read_b128 v[210:213], v203 offset:50176
	ds_read_b128 v[214:217], v203 offset:51200
	ds_read_b128 v[218:221], v203 offset:52224
	ds_read_b128 v[222:225], v203 offset:53248
	ds_read_b128 v[226:229], v203 offset:54272
	ds_read_b128 v[230:233], v203 offset:55296
	ds_read_b128 v[234:237], v203 offset:56320
	global_load_lds_dwordx4 v[238:239], off
	s_add_i32 m0, s23, 0x2000
	s_add_u32 s24, s48, 0x80080
	v_lshl_add_u64 v[238:239], v[240:241], 0, s[34:35]
	s_addc_u32 s25, s49, 0
	s_add_i32 s23, s86, s52
	global_load_lds_dwordx4 v[238:239], off
	v_lshl_add_u64 v[238:239], s[24:25], 0, v[130:131]
	s_mov_b32 m0, s23
	s_nop 0
	global_load_lds_dwordx4 v[238:239], off
	v_lshl_add_u64 v[238:239], s[24:25], 0, v[134:135]
	s_add_i32 m0, s23, 0x2000
	s_nop 0
	global_load_lds_dwordx4 v[238:239], off
	v_lshl_add_u64 v[238:239], v[242:243], 0, s[34:35]
	s_mov_b32 m0, s64
	s_nop 0
	global_load_lds_dwordx4 v[238:239], off
	v_lshl_add_u64 v[238:239], v[244:245], 0, s[34:35]
	s_mov_b32 m0, s65
	s_nop 0
	global_load_lds_dwordx4 v[238:239], off
	s_waitcnt vmcnt(8)
	s_waitcnt lgkmcnt(0)
	s_setprio 1
	s_barrier
	v_mfma_f32_16x16x32_bf16 v[60:63], v[158:161], v[206:209], v[60:63]
	v_mfma_f32_16x16x32_bf16 v[52:55], v[166:169], v[206:209], v[52:55]
	v_mfma_f32_16x16x32_bf16 v[44:47], v[158:161], v[214:217], v[44:47]
	v_mfma_f32_16x16x32_bf16 v[36:39], v[166:169], v[214:217], v[36:39]
	v_mfma_f32_16x16x32_bf16 v[28:31], v[158:161], v[222:225], v[28:31]
	v_mfma_f32_16x16x32_bf16 v[20:23], v[166:169], v[222:225], v[20:23]
	v_mfma_f32_16x16x32_bf16 v[12:15], v[158:161], v[230:233], v[12:15]
	v_mfma_f32_16x16x32_bf16 v[4:7], v[166:169], v[230:233], v[4:7]
	v_mfma_f32_16x16x32_bf16 v[60:63], v[162:165], v[210:213], v[60:63]
	v_mfma_f32_16x16x32_bf16 v[52:55], v[170:173], v[210:213], v[52:55]
	v_mfma_f32_16x16x32_bf16 v[44:47], v[162:165], v[218:221], v[44:47]
	v_mfma_f32_16x16x32_bf16 v[36:39], v[170:173], v[218:221], v[36:39]
	v_mfma_f32_16x16x32_bf16 v[28:31], v[162:165], v[226:229], v[28:31]
	v_mfma_f32_16x16x32_bf16 v[20:23], v[170:173], v[226:229], v[20:23]
	v_mfma_f32_16x16x32_bf16 v[12:15], v[162:165], v[234:237], v[12:15]
	v_mfma_f32_16x16x32_bf16 v[4:7], v[170:173], v[234:237], v[4:7]
	s_setprio 0
	s_setprio 1
	v_mfma_f32_16x16x32_bf16 v[56:59], v[174:177], v[206:209], v[56:59]
	v_mfma_f32_16x16x32_bf16 v[48:51], v[182:185], v[206:209], v[48:51]
	v_mfma_f32_16x16x32_bf16 v[40:43], v[174:177], v[214:217], v[40:43]
	v_mfma_f32_16x16x32_bf16 v[32:35], v[182:185], v[214:217], v[32:35]
	v_mfma_f32_16x16x32_bf16 v[24:27], v[174:177], v[222:225], v[24:27]
	v_mfma_f32_16x16x32_bf16 v[16:19], v[182:185], v[222:225], v[16:19]
	v_mfma_f32_16x16x32_bf16 v[8:11], v[174:177], v[230:233], v[8:11]
	v_mfma_f32_16x16x32_bf16 v[0:3], v[182:185], v[230:233], v[0:3]
	v_mfma_f32_16x16x32_bf16 v[56:59], v[178:181], v[210:213], v[56:59]
	v_mfma_f32_16x16x32_bf16 v[48:51], v[186:189], v[210:213], v[48:51]
	v_mfma_f32_16x16x32_bf16 v[40:43], v[178:181], v[218:221], v[40:43]
	v_mfma_f32_16x16x32_bf16 v[32:35], v[186:189], v[218:221], v[32:35]
	v_mfma_f32_16x16x32_bf16 v[24:27], v[178:181], v[226:229], v[24:27]
	v_mfma_f32_16x16x32_bf16 v[16:19], v[186:189], v[226:229], v[16:19]
	v_mfma_f32_16x16x32_bf16 v[8:11], v[178:181], v[234:237], v[8:11]
	v_mfma_f32_16x16x32_bf16 v[0:3], v[186:189], v[234:237], v[0:3]
	s_barrier
	s_setprio 0
	s_add_i32 s22, s22, 2
	s_add_u32 s46, s46, 0x100
	s_addc_u32 s47, s47, 0
	s_add_u32 vcc_hi, vcc_hi, 0x100
	s_addc_u32 s97, s97, 0
	s_cmp_gt_u32 s22, 29
	s_cbranch_scc0 .LBB0_129
	s_and_b64 vcc, exec, s[74:75]
	s_cbranch_vccz .LBB0_132
	s_barrier

; #define PG8_STAGE(bufoff, gbase, voff) do { _Pragma("unroll") for (int _i = 0; _i < 2; ++_i) \
;         __builtin_amdgcn_global_load_lds((const unsigned*)((const char*)(gbase) + (voff)[_i]), (PG8_LAS unsigned*)(lds + (bufoff) + ldsw + _i * 8192), 16, 0, 0); } while (0)
; #define PG8_LDA(dst, b, h) do { _Pragma("unroll") for (int m = 0; m < 4; ++m) _Pragma("unroll") for (int k = 0; k < 2; ++k) dst[m][k] = *(const PG8_LAS bf16x8*)(lds + PG8_SA(b, h) + aoff + m * 2048 + k * 1024); } while (0)
; #define PG8_LDB(dst, b, h) do { _Pragma("unroll") for (int n = 0; n < 2; ++n) _Pragma("unroll") for (int k = 0; k < 2; ++k) dst[n][k] = *(const PG8_LAS bf16x8*)(lds + PG8_SB(b, h) + boff + n * 2048 + k * 1024); } while (0)
; #define PG8_MMA(ai, bj, At, Bt) do { __builtin_amdgcn_s_setprio(1); _Pragma("unroll") for (int m = 0; m < 4; ++m) _Pragma("unroll") for (int n = 0; n < 2; ++n) _Pragma("unroll") for (int k = 0; k < 2; ++k) \
;         acc[ai][bj][m][n] = __builtin_amdgcn_mfma_f32_16x16x32_bf16(Bt[n][k], At[m][k], acc[ai][bj][m][n], 0, 0, 0); __builtin_amdgcn_s_setprio(0); } while (0)
; #define PG8_WAIT_V(n) asm volatile("s_waitcnt vmcnt(" #n ")" ::: "memory")
; #define PG8_WAIT_L(n) asm volatile("s_waitcnt lgkmcnt(" #n ")" ::: "memory")
; template <class Epi, class Sched, bool ALIGN_EPI = false, bool SP2 = false>
; __device__ __forceinline__ void gemm_phase(PG8_LAS unsigned char* lds, const Gemm g, const Sched& S, const Epi& E, const int wave_) {
;     ...
;             const bool last = (t == nt - 2);
;             const char* a1 = cA + (size_t)(t + 1) * kstep;
;             const char* a2 = last ? nA : cA + (size_t)(t + 2) * kstep; const char* b2 = last ? nB : cB + (size_t)(t + 2) * kstep;
;             const char* a3 = a2 + kstep; const char* b3 = b2 + kstep;
;             if (last && has_next) S.a_ready(nxt);
;             if constexpr (SP2) {
;             PG8_LDB(B0, 0, 0); PG8_LDB(B1, 0, 1); PG8_SCHED; PG8_LDA(At, 0, 0); PG8_STAGE(PG8_SA(1, 1), a1 + hstep, voffA);
;             PG8_WAIT_V(8); PG8_WAIT_L(0); PG8_BAR; PG8_MMA(0, 0, At, B0); PG8_MMA(0, 1, At, B1); PG8_BAR; PG8_SCHED;
;             PG8_LDA(At, 0, 1); PG8_STAGE(PG8_SB(0, 0), b2, voffB); PG8_STAGE(PG8_SB(0, 1), b2 + hstep, voffB); PG8_STAGE(PG8_SA(0, 0), a2, voffA);
;             PG8_WAIT_V(8); PG8_WAIT_L(0); PG8_BAR; PG8_MMA(1, 0, At, B0); PG8_MMA(1, 1, At, B1); PG8_BAR; PG8_SCHED;
.LBB0_402:
	ds_read_b128 v[128:131], v189
	ds_read_b128 v[132:135], v189 offset:1024
	ds_read_b128 v[136:139], v189 offset:2048
	ds_read_b128 v[140:143], v189 offset:3072
	ds_read_b128 v[144:147], v201
	ds_read_b128 v[148:151], v201 offset:1024
	ds_read_b128 v[180:183], v201 offset:2048
	ds_read_b128 v[184:187], v201 offset:3072
	s_add_u32 s30, s28, 0xfff00080
	s_addc_u32 s31, s29, -1
	s_cmp_eq_u32 s53, 60
	s_cselect_b32 s35, s19, s31
	s_cselect_b32 s34, s25, s30
	s_cselect_b32 s31, s17, s52
	s_cselect_b32 s30, s50, s51
	v_lshl_add_u64 v[170:171], s[28:29], 0, v[162:163]
	s_add_i32 m0, s27, 0xc000
	ds_read_b128 v[190:193], v202
	ds_read_b128 v[196:199], v202 offset:1024
	ds_read_b128 v[204:207], v202 offset:2048
	ds_read_b128 v[208:211], v202 offset:3072
	ds_read_b128 v[212:215], v202 offset:4096
	ds_read_b128 v[216:219], v202 offset:5120
	ds_read_b128 v[220:223], v202 offset:6144
	ds_read_b128 v[224:227], v202 offset:7168
	global_load_lds_dwordx4 v[170:171], off
	v_lshl_add_u64 v[170:171], s[28:29], 0, v[164:165]
	s_add_i32 m0, s27, 0xe000
	s_nop 0
	global_load_lds_dwordx4 v[170:171], off
	s_waitcnt vmcnt(8)
	s_waitcnt lgkmcnt(0)
	s_setprio 1
	s_barrier
	v_mfma_f32_16x16x32_bf16 v[124:127], v[128:131], v[190:193], v[124:127]
	v_mfma_f32_16x16x32_bf16 v[120:123], v[136:139], v[190:193], v[120:123]
	v_mfma_f32_16x16x32_bf16 v[108:111], v[128:131], v[204:207], v[108:111]
	v_mfma_f32_16x16x32_bf16 v[104:107], v[136:139], v[204:207], v[104:107]
	v_mfma_f32_16x16x32_bf16 v[92:95], v[128:131], v[212:215], v[92:95]
	v_mfma_f32_16x16x32_bf16 v[88:91], v[136:139], v[212:215], v[88:91]
	v_mfma_f32_16x16x32_bf16 v[76:79], v[128:131], v[220:223], v[76:79]
	v_mfma_f32_16x16x32_bf16 v[72:75], v[136:139], v[220:223], v[72:75]
	v_mfma_f32_16x16x32_bf16 v[124:127], v[132:135], v[196:199], v[124:127]
	v_mfma_f32_16x16x32_bf16 v[120:123], v[140:143], v[196:199], v[120:123]
	v_mfma_f32_16x16x32_bf16 v[108:111], v[132:135], v[208:211], v[108:111]
	v_mfma_f32_16x16x32_bf16 v[104:107], v[140:143], v[208:211], v[104:107]
	v_mfma_f32_16x16x32_bf16 v[92:95], v[132:135], v[216:219], v[92:95]
	v_mfma_f32_16x16x32_bf16 v[88:91], v[140:143], v[216:219], v[88:91]
	v_mfma_f32_16x16x32_bf16 v[76:79], v[132:135], v[224:227], v[76:79]
	v_mfma_f32_16x16x32_bf16 v[72:75], v[140:143], v[224:227], v[72:75]
	s_setprio 0
	s_setprio 1
	v_mfma_f32_16x16x32_bf16 v[116:119], v[144:147], v[190:193], v[116:119]
	v_mfma_f32_16x16x32_bf16 v[112:115], v[180:183], v[190:193], v[112:115]
	v_mfma_f32_16x16x32_bf16 v[100:103], v[144:147], v[204:207], v[100:103]
	v_mfma_f32_16x16x32_bf16 v[96:99], v[180:183], v[204:207], v[96:99]
	v_mfma_f32_16x16x32_bf16 v[84:87], v[144:147], v[212:215], v[84:87]
	v_mfma_f32_16x16x32_bf16 v[80:83], v[180:183], v[212:215], v[80:83]
	v_mfma_f32_16x16x32_bf16 v[68:71], v[144:147], v[220:223], v[68:71]
	v_mfma_f32_16x16x32_bf16 v[64:67], v[180:183], v[220:223], v[64:67]
	v_mfma_f32_16x16x32_bf16 v[116:119], v[148:151], v[196:199], v[116:119]
	v_mfma_f32_16x16x32_bf16 v[112:115], v[184:187], v[196:199], v[112:115]
	v_mfma_f32_16x16x32_bf16 v[100:103], v[148:151], v[208:211], v[100:103]
	v_mfma_f32_16x16x32_bf16 v[96:99], v[184:187], v[208:211], v[96:99]
	v_mfma_f32_16x16x32_bf16 v[84:87], v[148:151], v[216:219], v[84:87]
	v_mfma_f32_16x16x32_bf16 v[80:83], v[184:187], v[216:219], v[80:83]
	v_mfma_f32_16x16x32_bf16 v[68:71], v[148:151], v[224:227], v[68:71]
	v_mfma_f32_16x16x32_bf16 v[64:67], v[184:187], v[224:227], v[64:67]
	s_barrier
	s_setprio 0
	s_add_i32 s54, s48, s36
	v_lshl_add_u64 v[170:171], s[30:31], 0, v[156:157]
	s_mov_b32 m0, s54
	ds_read_b128 v[190:193], v202 offset:16384
	ds_read_b128 v[196:199], v202 offset:17408
	ds_read_b128 v[204:207], v202 offset:18432
	ds_read_b128 v[208:211], v202 offset:19456
	ds_read_b128 v[212:215], v202 offset:20480
	ds_read_b128 v[216:219], v202 offset:21504
	ds_read_b128 v[220:223], v202 offset:22528
	ds_read_b128 v[224:227], v202 offset:23552
	global_load_lds_dwordx4 v[170:171], off
	s_add_i32 m0, s54, 0x2000
	s_add_u32 s54, s30, 0x100000
	v_lshl_add_u64 v[228:229], s[30:31], 0, v[160:161]
	s_addc_u32 s55, s31, 0
	s_add_i32 s56, s49, s36
	global_load_lds_dwordx4 v[228:229], off
	v_lshl_add_u64 v[230:231], s[54:55], 0, v[156:157]
	s_mov_b32 m0, s56
	v_lshl_add_u64 v[232:233], s[34:35], 0, v[158:159]
	global_load_lds_dwordx4 v[230:231], off
	v_lshl_add_u64 v[230:231], s[54:55], 0, v[160:161]
	s_add_i32 m0, s56, 0x2000
	s_nop 0
	global_load_lds_dwordx4 v[230:231], off
	v_lshl_add_u64 v[230:231], s[34:35], 0, v[154:155]
	s_mov_b32 m0, s27
	s_nop 0
	global_load_lds_dwordx4 v[230:231], off
	s_mov_b32 m0, s37
	s_nop 0
	global_load_lds_dwordx4 v[232:233], off
	s_waitcnt vmcnt(8)
	s_waitcnt lgkmcnt(0)
	s_setprio 1
	s_barrier
; #define PG8_STAGE(bufoff, gbase, voff) do { _Pragma("unroll") for (int _i = 0; _i < 2; ++_i) \
;         __builtin_amdgcn_global_load_lds((const unsigned*)((const char*)(gbase) + (voff)[_i]), (PG8_LAS unsigned*)(lds + (bufoff) + ldsw + _i * 8192), 16, 0, 0); } while (0)
; #define PG8_LDA(dst, b, h) do { _Pragma("unroll") for (int m = 0; m < 4; ++m) _Pragma("unroll") for (int k = 0; k < 2; ++k) dst[m][k] = *(const PG8_LAS bf16x8*)(lds + PG8_SA(b, h) + aoff + m * 2048 + k * 1024); } while (0)
; #define PG8_LDB(dst, b, h) do { _Pragma("unroll") for (int n = 0; n < 2; ++n) _Pragma("unroll") for (int k = 0; k < 2; ++k) dst[n][k] = *(const PG8_LAS bf16x8*)(lds + PG8_SB(b, h) + boff + n * 2048 + k * 1024); } while (0)
; #define PG8_MMA(ai, bj, At, Bt) do { __builtin_amdgcn_s_setprio(1); _Pragma("unroll") for (int m = 0; m < 4; ++m) _Pragma("unroll") for (int n = 0; n < 2; ++n) _Pragma("unroll") for (int k = 0; k < 2; ++k) \
;         acc[ai][bj][m][n] = __builtin_amdgcn_mfma_f32_16x16x32_bf16(Bt[n][k], At[m][k], acc[ai][bj][m][n], 0, 0, 0); __builtin_amdgcn_s_setprio(0); } while (0)
; #define PG8_WAIT_V(n) asm volatile("s_waitcnt vmcnt(" #n ")" ::: "memory")
; #define PG8_WAIT_L(n) asm volatile("s_waitcnt lgkmcnt(" #n ")" ::: "memory")
; #define PG8_BAR __builtin_amdgcn_s_barrier()
; #define PG8_SCHED __builtin_amdgcn_sched_barrier(0)
; template <class Epi, class Sched, bool ALIGN_EPI = false, bool SP2 = false>
; __device__ __forceinline__ void gemm_phase(PG8_LAS unsigned char* lds, const Gemm g, const Sched& S, const Epi& E, const int wave_) {
;     ...
;             PG8_WAIT_V(8); PG8_WAIT_L(0); PG8_BAR; PG8_MMA(1, 0, At, B0); PG8_MMA(1, 1, At, B1); PG8_BAR; PG8_SCHED;
;             PG8_LDB(B0, 1, 0); PG8_LDB(B1, 1, 1); PG8_SCHED; PG8_LDA(At, 1, 0); PG8_STAGE(PG8_SA(0, 1), a2 + hstep, voffA);
;             PG8_WAIT_V(8); PG8_WAIT_L(0); PG8_BAR; PG8_MMA(0, 0, At, B0); PG8_MMA(0, 1, At, B1); PG8_BAR; PG8_SCHED;
	v_mfma_f32_16x16x32_bf16 v[60:63], v[128:131], v[190:193], v[60:63]
	v_mfma_f32_16x16x32_bf16 v[56:59], v[136:139], v[190:193], v[56:59]
	v_mfma_f32_16x16x32_bf16 v[44:47], v[128:131], v[204:207], v[44:47]
	v_mfma_f32_16x16x32_bf16 v[40:43], v[136:139], v[204:207], v[40:43]
	v_mfma_f32_16x16x32_bf16 v[28:31], v[128:131], v[212:215], v[28:31]
	v_mfma_f32_16x16x32_bf16 v[24:27], v[136:139], v[212:215], v[24:27]
	v_mfma_f32_16x16x32_bf16 v[12:15], v[128:131], v[220:223], v[12:15]
	v_mfma_f32_16x16x32_bf16 v[8:11], v[136:139], v[220:223], v[8:11]
	v_mfma_f32_16x16x32_bf16 v[60:63], v[132:135], v[196:199], v[60:63]
	v_mfma_f32_16x16x32_bf16 v[56:59], v[140:143], v[196:199], v[56:59]
	v_mfma_f32_16x16x32_bf16 v[44:47], v[132:135], v[208:211], v[44:47]
	v_mfma_f32_16x16x32_bf16 v[40:43], v[140:143], v[208:211], v[40:43]
	v_mfma_f32_16x16x32_bf16 v[28:31], v[132:135], v[216:219], v[28:31]
	v_mfma_f32_16x16x32_bf16 v[24:27], v[140:143], v[216:219], v[24:27]
	v_mfma_f32_16x16x32_bf16 v[12:15], v[132:135], v[224:227], v[12:15]
	v_mfma_f32_16x16x32_bf16 v[8:11], v[140:143], v[224:227], v[8:11]
	s_setprio 0
	s_setprio 1
	v_mfma_f32_16x16x32_bf16 v[52:55], v[144:147], v[190:193], v[52:55]
	v_mfma_f32_16x16x32_bf16 v[48:51], v[180:183], v[190:193], v[48:51]
	v_mfma_f32_16x16x32_bf16 v[36:39], v[144:147], v[204:207], v[36:39]
	v_mfma_f32_16x16x32_bf16 v[32:35], v[180:183], v[204:207], v[32:35]
	v_mfma_f32_16x16x32_bf16 v[20:23], v[144:147], v[212:215], v[20:23]
	v_mfma_f32_16x16x32_bf16 v[16:19], v[180:183], v[212:215], v[16:19]
	v_mfma_f32_16x16x32_bf16 v[4:7], v[144:147], v[220:223], v[4:7]
	v_mfma_f32_16x16x32_bf16 v[0:3], v[180:183], v[220:223], v[0:3]
	v_mfma_f32_16x16x32_bf16 v[52:55], v[148:151], v[196:199], v[52:55]
	v_mfma_f32_16x16x32_bf16 v[48:51], v[184:187], v[196:199], v[48:51]
	v_mfma_f32_16x16x32_bf16 v[36:39], v[148:151], v[208:211], v[36:39]
	v_mfma_f32_16x16x32_bf16 v[32:35], v[184:187], v[208:211], v[32:35]
	v_mfma_f32_16x16x32_bf16 v[20:23], v[148:151], v[216:219], v[20:23]
	v_mfma_f32_16x16x32_bf16 v[16:19], v[184:187], v[216:219], v[16:19]
	v_mfma_f32_16x16x32_bf16 v[4:7], v[148:151], v[224:227], v[4:7]
	v_mfma_f32_16x16x32_bf16 v[0:3], v[184:187], v[224:227], v[0:3]
	s_barrier
	s_setprio 0
	s_add_i32 s54, 0, 0x18000
	s_add_i32 s55, 0, 0x1c000
	v_add_u32_e32 v140, s54, v173
	v_add_u32_e32 v172, s55, v173
	ds_read_b128 v[128:131], v140
	ds_read_b128 v[132:135], v140 offset:1024
	ds_read_b128 v[136:139], v140 offset:2048
	ds_read_b128 v[140:143], v140 offset:3072
	ds_read_b128 v[144:147], v172
	ds_read_b128 v[148:151], v172 offset:1024
	ds_read_b128 v[180:183], v172 offset:2048
	ds_read_b128 v[184:187], v172 offset:3072
	s_add_u32 s34, s34, 0x100000
	s_addc_u32 s35, s35, 0
	s_mov_b32 m0, s40
	v_lshl_add_u64 v[234:235], s[34:35], 0, v[154:155]
	ds_read_b128 v[190:193], v202 offset:32768
	ds_read_b128 v[196:199], v202 offset:33792
	ds_read_b128 v[204:207], v202 offset:34816
	ds_read_b128 v[208:211], v202 offset:35840
	ds_read_b128 v[212:215], v202 offset:36864
	ds_read_b128 v[216:219], v202 offset:37888
	ds_read_b128 v[220:223], v202 offset:38912
	ds_read_b128 v[224:227], v202 offset:39936
	global_load_lds_dwordx4 v[234:235], off
	v_lshl_add_u64 v[234:235], s[34:35], 0, v[158:159]
	s_mov_b32 m0, s41
	s_nop 0
	global_load_lds_dwordx4 v[234:235], off
	s_waitcnt vmcnt(8)
	s_waitcnt lgkmcnt(0)
	s_setprio 1
	s_barrier
	v_mfma_f32_16x16x32_bf16 v[124:127], v[128:131], v[190:193], v[124:127]
	v_mfma_f32_16x16x32_bf16 v[120:123], v[136:139], v[190:193], v[120:123]
	v_mfma_f32_16x16x32_bf16 v[108:111], v[128:131], v[204:207], v[108:111]
	v_mfma_f32_16x16x32_bf16 v[104:107], v[136:139], v[204:207], v[104:107]
	v_mfma_f32_16x16x32_bf16 v[92:95], v[128:131], v[212:215], v[92:95]
	v_mfma_f32_16x16x32_bf16 v[88:91], v[136:139], v[212:215], v[88:91]
	v_mfma_f32_16x16x32_bf16 v[76:79], v[128:131], v[220:223], v[76:79]
	v_mfma_f32_16x16x32_bf16 v[72:75], v[136:139], v[220:223], v[72:75]
	v_mfma_f32_16x16x32_bf16 v[124:127], v[132:135], v[196:199], v[124:127]
	v_mfma_f32_16x16x32_bf16 v[120:123], v[140:143], v[196:199], v[120:123]
	v_mfma_f32_16x16x32_bf16 v[108:111], v[132:135], v[208:211], v[108:111]
	v_mfma_f32_16x16x32_bf16 v[104:107], v[140:143], v[208:211], v[104:107]
	v_mfma_f32_16x16x32_bf16 v[92:95], v[132:135], v[216:219], v[92:95]
	v_mfma_f32_16x16x32_bf16 v[88:91], v[140:143], v[216:219], v[88:91]
	v_mfma_f32_16x16x32_bf16 v[76:79], v[132:135], v[224:227], v[76:79]
	v_mfma_f32_16x16x32_bf16 v[72:75], v[140:143], v[224:227], v[72:75]
	s_setprio 0
	s_setprio 1
	v_mfma_f32_16x16x32_bf16 v[116:119], v[144:147], v[190:193], v[116:119]
	v_mfma_f32_16x16x32_bf16 v[112:115], v[180:183], v[190:193], v[112:115]
	v_mfma_f32_16x16x32_bf16 v[100:103], v[144:147], v[204:207], v[100:103]
	v_mfma_f32_16x16x32_bf16 v[96:99], v[180:183], v[204:207], v[96:99]
	v_mfma_f32_16x16x32_bf16 v[84:87], v[144:147], v[212:215], v[84:87]
	v_mfma_f32_16x16x32_bf16 v[80:83], v[180:183], v[212:215], v[80:83]
	v_mfma_f32_16x16x32_bf16 v[68:71], v[144:147], v[220:223], v[68:71]
	v_mfma_f32_16x16x32_bf16 v[64:67], v[180:183], v[220:223], v[64:67]
	v_mfma_f32_16x16x32_bf16 v[116:119], v[148:151], v[196:199], v[116:119]
	v_mfma_f32_16x16x32_bf16 v[112:115], v[184:187], v[196:199], v[112:115]
	v_mfma_f32_16x16x32_bf16 v[100:103], v[148:151], v[208:211], v[100:103]
	v_mfma_f32_16x16x32_bf16 v[96:99], v[184:187], v[208:211], v[96:99]
	v_mfma_f32_16x16x32_bf16 v[84:87], v[148:151], v[216:219], v[84:87]
	v_mfma_f32_16x16x32_bf16 v[80:83], v[184:187], v[216:219], v[80:83]
	v_mfma_f32_16x16x32_bf16 v[68:71], v[148:151], v[224:227], v[68:71]
	v_mfma_f32_16x16x32_bf16 v[64:67], v[184:187], v[224:227], v[64:67]
	s_barrier
; #define PG8_STAGE(bufoff, gbase, voff) do { _Pragma("unroll") for (int _i = 0; _i < 2; ++_i) \
;         __builtin_amdgcn_global_load_lds((const unsigned*)((const char*)(gbase) + (voff)[_i]), (PG8_LAS unsigned*)(lds + (bufoff) + ldsw + _i * 8192), 16, 0, 0); } while (0)
; #define PG8_LDA(dst, b, h) do { _Pragma("unroll") for (int m = 0; m < 4; ++m) _Pragma("unroll") for (int k = 0; k < 2; ++k) dst[m][k] = *(const PG8_LAS bf16x8*)(lds + PG8_SA(b, h) + aoff + m * 2048 + k * 1024); } while (0)
; #define PG8_MMA(ai, bj, At, Bt) do { __builtin_amdgcn_s_setprio(1); _Pragma("unroll") for (int m = 0; m < 4; ++m) _Pragma("unroll") for (int n = 0; n < 2; ++n) _Pragma("unroll") for (int k = 0; k < 2; ++k) \
;         acc[ai][bj][m][n] = __builtin_amdgcn_mfma_f32_16x16x32_bf16(Bt[n][k], At[m][k], acc[ai][bj][m][n], 0, 0, 0); __builtin_amdgcn_s_setprio(0); } while (0)
; #define PG8_WAIT_V(n) asm volatile("s_waitcnt vmcnt(" #n ")" ::: "memory")
; #define PG8_WAIT_L(n) asm volatile("s_waitcnt lgkmcnt(" #n ")" ::: "memory")
; #define PG8_BAR __builtin_amdgcn_s_barrier()
; #define PG8_SCHED __builtin_amdgcn_sched_barrier(0)
; template <class Epi, class Sched, bool ALIGN_EPI = false, bool SP2 = false>
; __device__ __forceinline__ void gemm_phase(PG8_LAS unsigned char* lds, const Gemm g, const Sched& S, const Epi& E, const int wave_) {
;     ...
;         for (int t = 0; t < nt; t += 2) {
;     ...
;             PG8_LDA(At, 1, 1); PG8_STAGE(PG8_SB(1, 0), b3, voffB); PG8_STAGE(PG8_SB(1, 1), b3 + hstep, voffB); PG8_STAGE(PG8_SA(1, 0), a3, voffA);
;             PG8_WAIT_V(8); PG8_WAIT_L(0); PG8_BAR; PG8_MMA(1, 0, At, B0); PG8_MMA(1, 1, At, B1); PG8_BAR; PG8_SCHED;
	s_setprio 0
	s_add_i32 s34, s54, s36
	v_lshl_add_u64 v[170:171], v[170:171], 0, s[14:15]
	s_mov_b32 m0, s34
	ds_read_b128 v[190:193], v202 offset:49152
	ds_read_b128 v[196:199], v202 offset:50176
	ds_read_b128 v[204:207], v202 offset:51200
	ds_read_b128 v[208:211], v202 offset:52224
	ds_read_b128 v[212:215], v202 offset:53248
	ds_read_b128 v[216:219], v202 offset:54272
	ds_read_b128 v[220:223], v202 offset:55296
	ds_read_b128 v[224:227], v202 offset:56320
	global_load_lds_dwordx4 v[170:171], off
	s_add_i32 m0, s34, 0x2000
	s_add_u32 s30, s30, 0x100080
	v_lshl_add_u64 v[170:171], v[228:229], 0, s[14:15]
	s_addc_u32 s31, s31, 0
	s_add_i32 s34, s55, s36
	global_load_lds_dwordx4 v[170:171], off
	v_lshl_add_u64 v[170:171], s[30:31], 0, v[156:157]
	s_mov_b32 m0, s34
	s_nop 0
	global_load_lds_dwordx4 v[170:171], off
	v_lshl_add_u64 v[170:171], s[30:31], 0, v[160:161]
	s_add_i32 m0, s34, 0x2000
	s_nop 0
	global_load_lds_dwordx4 v[170:171], off
	v_lshl_add_u64 v[170:171], v[230:231], 0, s[14:15]
	s_mov_b32 m0, s45
	s_nop 0
	global_load_lds_dwordx4 v[170:171], off
	v_lshl_add_u64 v[170:171], v[232:233], 0, s[14:15]
	s_mov_b32 m0, s46
	s_nop 0
	global_load_lds_dwordx4 v[170:171], off
	s_waitcnt vmcnt(8)
	s_waitcnt lgkmcnt(0)
	s_setprio 1
	s_barrier
	v_mfma_f32_16x16x32_bf16 v[60:63], v[128:131], v[190:193], v[60:63]
	v_mfma_f32_16x16x32_bf16 v[56:59], v[136:139], v[190:193], v[56:59]
	v_mfma_f32_16x16x32_bf16 v[44:47], v[128:131], v[204:207], v[44:47]
	v_mfma_f32_16x16x32_bf16 v[40:43], v[136:139], v[204:207], v[40:43]
	v_mfma_f32_16x16x32_bf16 v[28:31], v[128:131], v[212:215], v[28:31]
	v_mfma_f32_16x16x32_bf16 v[24:27], v[136:139], v[212:215], v[24:27]
	v_mfma_f32_16x16x32_bf16 v[12:15], v[128:131], v[220:223], v[12:15]
	v_mfma_f32_16x16x32_bf16 v[8:11], v[136:139], v[220:223], v[8:11]
	v_mfma_f32_16x16x32_bf16 v[60:63], v[132:135], v[196:199], v[60:63]
	v_mfma_f32_16x16x32_bf16 v[56:59], v[140:143], v[196:199], v[56:59]
	v_mfma_f32_16x16x32_bf16 v[44:47], v[132:135], v[208:211], v[44:47]
	v_mfma_f32_16x16x32_bf16 v[40:43], v[140:143], v[208:211], v[40:43]
	v_mfma_f32_16x16x32_bf16 v[28:31], v[132:135], v[216:219], v[28:31]
	v_mfma_f32_16x16x32_bf16 v[24:27], v[140:143], v[216:219], v[24:27]
	v_mfma_f32_16x16x32_bf16 v[12:15], v[132:135], v[224:227], v[12:15]
	v_mfma_f32_16x16x32_bf16 v[8:11], v[140:143], v[224:227], v[8:11]
	s_setprio 0
	s_setprio 1
	v_mfma_f32_16x16x32_bf16 v[52:55], v[144:147], v[190:193], v[52:55]
	v_mfma_f32_16x16x32_bf16 v[48:51], v[180:183], v[190:193], v[48:51]
	v_mfma_f32_16x16x32_bf16 v[36:39], v[144:147], v[204:207], v[36:39]
	v_mfma_f32_16x16x32_bf16 v[32:35], v[180:183], v[204:207], v[32:35]
	v_mfma_f32_16x16x32_bf16 v[20:23], v[144:147], v[212:215], v[20:23]
	v_mfma_f32_16x16x32_bf16 v[16:19], v[180:183], v[212:215], v[16:19]
	v_mfma_f32_16x16x32_bf16 v[4:7], v[144:147], v[220:223], v[4:7]
	v_mfma_f32_16x16x32_bf16 v[0:3], v[180:183], v[220:223], v[0:3]
	v_mfma_f32_16x16x32_bf16 v[52:55], v[148:151], v[196:199], v[52:55]
	v_mfma_f32_16x16x32_bf16 v[48:51], v[184:187], v[196:199], v[48:51]
	v_mfma_f32_16x16x32_bf16 v[36:39], v[148:151], v[208:211], v[36:39]
	v_mfma_f32_16x16x32_bf16 v[32:35], v[184:187], v[208:211], v[32:35]
	v_mfma_f32_16x16x32_bf16 v[20:23], v[148:151], v[216:219], v[20:23]
	v_mfma_f32_16x16x32_bf16 v[16:19], v[184:187], v[216:219], v[16:19]
	v_mfma_f32_16x16x32_bf16 v[4:7], v[148:151], v[224:227], v[4:7]
	v_mfma_f32_16x16x32_bf16 v[0:3], v[184:187], v[224:227], v[0:3]
	s_barrier
	s_setprio 0
	s_add_i32 s53, s53, 2
	s_add_u32 s28, s28, 0x100
	s_addc_u32 s29, s29, 0
	s_add_u32 s51, s51, 0x100
	s_addc_u32 s52, s52, 0
	s_cmp_gt_u32 s53, 61
	s_cbranch_scc0 .LBB0_402
	s_and_b64 vcc, exec, s[12:13]
	s_cbranch_vccz .LBB0_405
	s_barrier

; #define PG8_STAGE(bufoff, gbase, voff) do { _Pragma("unroll") for (int _i = 0; _i < 2; ++_i) \
;         __builtin_amdgcn_global_load_lds((const unsigned*)((const char*)(gbase) + (voff)[_i]), (PG8_LAS unsigned*)(lds + (bufoff) + ldsw + _i * 8192), 16, 0, 0); } while (0)
; #define PG8_LDA(dst, b, h) do { _Pragma("unroll") for (int m = 0; m < 4; ++m) _Pragma("unroll") for (int k = 0; k < 2; ++k) dst[m][k] = *(const PG8_LAS bf16x8*)(lds + PG8_SA(b, h) + aoff + m * 2048 + k * 1024); } while (0)
; #define PG8_LDB(dst, b, h) do { _Pragma("unroll") for (int n = 0; n < 2; ++n) _Pragma("unroll") for (int k = 0; k < 2; ++k) dst[n][k] = *(const PG8_LAS bf16x8*)(lds + PG8_SB(b, h) + boff + n * 2048 + k * 1024); } while (0)
; #define PG8_MMA(ai, bj, At, Bt) do { __builtin_amdgcn_s_setprio(1); _Pragma("unroll") for (int m = 0; m < 4; ++m) _Pragma("unroll") for (int n = 0; n < 2; ++n) _Pragma("unroll") for (int k = 0; k < 2; ++k) \
;         acc[ai][bj][m][n] = __builtin_amdgcn_mfma_f32_16x16x32_bf16(Bt[n][k], At[m][k], acc[ai][bj][m][n], 0, 0, 0); __builtin_amdgcn_s_setprio(0); } while (0)
; #define PG8_WAIT_V(n) asm volatile("s_waitcnt vmcnt(" #n ")" ::: "memory")
; #define PG8_WAIT_L(n) asm volatile("s_waitcnt lgkmcnt(" #n ")" ::: "memory")
; template <class Epi, class Sched, bool ALIGN_EPI = false, bool SP2 = false>
; __device__ __forceinline__ void gemm_phase(PG8_LAS unsigned char* lds, const Gemm g, const Sched& S, const Epi& E, const int wave_) {
;     ...
;             const bool last = (t == nt - 2);
;             const char* a1 = cA + (size_t)(t + 1) * kstep;
;             const char* a2 = last ? nA : cA + (size_t)(t + 2) * kstep; const char* b2 = last ? nB : cB + (size_t)(t + 2) * kstep;
;             const char* a3 = a2 + kstep; const char* b3 = b2 + kstep;
;             if (last && has_next) S.a_ready(nxt);
;             if constexpr (SP2) {
;             PG8_LDB(B0, 0, 0); PG8_LDB(B1, 0, 1); PG8_SCHED; PG8_LDA(At, 0, 0); PG8_STAGE(PG8_SA(1, 1), a1 + hstep, voffA);
;             PG8_WAIT_V(8); PG8_WAIT_L(0); PG8_BAR; PG8_MMA(0, 0, At, B0); PG8_MMA(0, 1, At, B1); PG8_BAR; PG8_SCHED;
;             PG8_LDA(At, 0, 1); PG8_STAGE(PG8_SB(0, 0), b2, voffB); PG8_STAGE(PG8_SB(0, 1), b2 + hstep, voffB); PG8_STAGE(PG8_SA(0, 0), a2, voffA);
;             PG8_WAIT_V(8); PG8_WAIT_L(0); PG8_BAR; PG8_MMA(1, 0, At, B0); PG8_MMA(1, 1, At, B1); PG8_BAR; PG8_SCHED;
.LBB0_495:
	ds_read_b128 v[146:149], v164
	ds_read_b128 v[154:157], v164 offset:1024
	ds_read_b128 v[158:161], v164 offset:2048
	ds_read_b128 v[168:171], v164 offset:3072
	ds_read_b128 v[172:175], v165
	ds_read_b128 v[176:179], v165 offset:1024
	ds_read_b128 v[180:183], v165 offset:2048
	ds_read_b128 v[184:187], v165 offset:3072
	s_add_u32 s40, s36, 0xfff80080
	s_addc_u32 s41, s37, -1
	s_cmp_eq_u32 s63, 28
	s_cselect_b32 s43, s5, s41
	s_cselect_b32 s42, s7, s40
	s_cselect_b32 s41, s27, s62
	s_cselect_b32 s40, s29, s61
	v_lshl_add_u64 v[150:151], s[36:37], 0, v[138:139]
	s_add_i32 m0, s45, 0xc000
	ds_read_b128 v[188:191], v166
	ds_read_b128 v[196:199], v166 offset:1024
	ds_read_b128 v[200:203], v166 offset:2048
	ds_read_b128 v[204:207], v166 offset:3072
	ds_read_b128 v[208:211], v166 offset:4096
	ds_read_b128 v[212:215], v166 offset:5120
	ds_read_b128 v[216:219], v166 offset:6144
	ds_read_b128 v[220:223], v166 offset:7168
	global_load_lds_dwordx4 v[150:151], off
	v_lshl_add_u64 v[150:151], s[36:37], 0, v[140:141]
	s_add_i32 m0, s45, 0xe000
	s_nop 0
	global_load_lds_dwordx4 v[150:151], off
	s_waitcnt vmcnt(8)
	s_waitcnt lgkmcnt(0)
	s_setprio 1
	s_barrier
	v_mfma_f32_16x16x32_bf16 v[124:127], v[146:149], v[188:191], v[124:127]
	v_mfma_f32_16x16x32_bf16 v[120:123], v[158:161], v[188:191], v[120:123]
	v_mfma_f32_16x16x32_bf16 v[108:111], v[146:149], v[200:203], v[108:111]
	v_mfma_f32_16x16x32_bf16 v[104:107], v[158:161], v[200:203], v[104:107]
	v_mfma_f32_16x16x32_bf16 v[92:95], v[146:149], v[208:211], v[92:95]
	v_mfma_f32_16x16x32_bf16 v[88:91], v[158:161], v[208:211], v[88:91]
	v_mfma_f32_16x16x32_bf16 v[76:79], v[146:149], v[216:219], v[76:79]
	v_mfma_f32_16x16x32_bf16 v[72:75], v[158:161], v[216:219], v[72:75]
	v_mfma_f32_16x16x32_bf16 v[124:127], v[154:157], v[196:199], v[124:127]
	v_mfma_f32_16x16x32_bf16 v[120:123], v[168:171], v[196:199], v[120:123]
	v_mfma_f32_16x16x32_bf16 v[108:111], v[154:157], v[204:207], v[108:111]
	v_mfma_f32_16x16x32_bf16 v[104:107], v[168:171], v[204:207], v[104:107]
	v_mfma_f32_16x16x32_bf16 v[92:95], v[154:157], v[212:215], v[92:95]
	v_mfma_f32_16x16x32_bf16 v[88:91], v[168:171], v[212:215], v[88:91]
	v_mfma_f32_16x16x32_bf16 v[76:79], v[154:157], v[220:223], v[76:79]
	v_mfma_f32_16x16x32_bf16 v[72:75], v[168:171], v[220:223], v[72:75]
	s_setprio 0
	s_setprio 1
	v_mfma_f32_16x16x32_bf16 v[116:119], v[172:175], v[188:191], v[116:119]
	v_mfma_f32_16x16x32_bf16 v[112:115], v[180:183], v[188:191], v[112:115]
	v_mfma_f32_16x16x32_bf16 v[100:103], v[172:175], v[200:203], v[100:103]
	v_mfma_f32_16x16x32_bf16 v[96:99], v[180:183], v[200:203], v[96:99]
	v_mfma_f32_16x16x32_bf16 v[84:87], v[172:175], v[208:211], v[84:87]
	v_mfma_f32_16x16x32_bf16 v[80:83], v[180:183], v[208:211], v[80:83]
	v_mfma_f32_16x16x32_bf16 v[68:71], v[172:175], v[216:219], v[68:71]
	v_mfma_f32_16x16x32_bf16 v[64:67], v[180:183], v[216:219], v[64:67]
	v_mfma_f32_16x16x32_bf16 v[116:119], v[176:179], v[196:199], v[116:119]
	v_mfma_f32_16x16x32_bf16 v[112:115], v[184:187], v[196:199], v[112:115]
	v_mfma_f32_16x16x32_bf16 v[100:103], v[176:179], v[204:207], v[100:103]
	v_mfma_f32_16x16x32_bf16 v[96:99], v[184:187], v[204:207], v[96:99]
	v_mfma_f32_16x16x32_bf16 v[84:87], v[176:179], v[212:215], v[84:87]
	v_mfma_f32_16x16x32_bf16 v[80:83], v[184:187], v[212:215], v[80:83]
	v_mfma_f32_16x16x32_bf16 v[68:71], v[176:179], v[220:223], v[68:71]
	v_mfma_f32_16x16x32_bf16 v[64:67], v[184:187], v[220:223], v[64:67]
	s_barrier
	s_setprio 0
	s_add_i32 s64, s55, s44
	v_lshl_add_u64 v[150:151], s[40:41], 0, v[130:131]
	s_mov_b32 m0, s64
	ds_read_b128 v[188:191], v166 offset:16384
	ds_read_b128 v[196:199], v166 offset:17408
	ds_read_b128 v[200:203], v166 offset:18432
	ds_read_b128 v[204:207], v166 offset:19456
	ds_read_b128 v[208:211], v166 offset:20480
	ds_read_b128 v[212:215], v166 offset:21504
	ds_read_b128 v[216:219], v166 offset:22528
	ds_read_b128 v[220:223], v166 offset:23552
	global_load_lds_dwordx4 v[150:151], off
	s_add_i32 m0, s64, 0x2000
	s_add_u32 s64, s40, 0x80000
	v_lshl_add_u64 v[192:193], s[40:41], 0, v[134:135]
	s_addc_u32 s65, s41, 0
	s_add_i32 s66, s56, s44
	global_load_lds_dwordx4 v[192:193], off
	v_lshl_add_u64 v[224:225], s[64:65], 0, v[130:131]
	s_mov_b32 m0, s66
	v_lshl_add_u64 v[226:227], s[42:43], 0, v[132:133]
	global_load_lds_dwordx4 v[224:225], off
	v_lshl_add_u64 v[224:225], s[64:65], 0, v[134:135]
	s_add_i32 m0, s66, 0x2000
	s_nop 0
	global_load_lds_dwordx4 v[224:225], off
	v_lshl_add_u64 v[224:225], s[42:43], 0, v[128:129]
	s_mov_b32 m0, s45
	s_nop 0
	global_load_lds_dwordx4 v[224:225], off
	s_mov_b32 m0, s46
	s_nop 0
	global_load_lds_dwordx4 v[226:227], off
	s_waitcnt vmcnt(8)
	s_waitcnt lgkmcnt(0)
	s_setprio 1
	s_barrier
; #define PG8_STAGE(bufoff, gbase, voff) do { _Pragma("unroll") for (int _i = 0; _i < 2; ++_i) \
;         __builtin_amdgcn_global_load_lds((const unsigned*)((const char*)(gbase) + (voff)[_i]), (PG8_LAS unsigned*)(lds + (bufoff) + ldsw + _i * 8192), 16, 0, 0); } while (0)
; #define PG8_LDA(dst, b, h) do { _Pragma("unroll") for (int m = 0; m < 4; ++m) _Pragma("unroll") for (int k = 0; k < 2; ++k) dst[m][k] = *(const PG8_LAS bf16x8*)(lds + PG8_SA(b, h) + aoff + m * 2048 + k * 1024); } while (0)
; #define PG8_LDB(dst, b, h) do { _Pragma("unroll") for (int n = 0; n < 2; ++n) _Pragma("unroll") for (int k = 0; k < 2; ++k) dst[n][k] = *(const PG8_LAS bf16x8*)(lds + PG8_SB(b, h) + boff + n * 2048 + k * 1024); } while (0)
; #define PG8_MMA(ai, bj, At, Bt) do { __builtin_amdgcn_s_setprio(1); _Pragma("unroll") for (int m = 0; m < 4; ++m) _Pragma("unroll") for (int n = 0; n < 2; ++n) _Pragma("unroll") for (int k = 0; k < 2; ++k) \
;         acc[ai][bj][m][n] = __builtin_amdgcn_mfma_f32_16x16x32_bf16(Bt[n][k], At[m][k], acc[ai][bj][m][n], 0, 0, 0); __builtin_amdgcn_s_setprio(0); } while (0)
; #define PG8_WAIT_V(n) asm volatile("s_waitcnt vmcnt(" #n ")" ::: "memory")
; #define PG8_WAIT_L(n) asm volatile("s_waitcnt lgkmcnt(" #n ")" ::: "memory")
; #define PG8_BAR __builtin_amdgcn_s_barrier()
; #define PG8_SCHED __builtin_amdgcn_sched_barrier(0)
; template <class Epi, class Sched, bool ALIGN_EPI = false, bool SP2 = false>
; __device__ __forceinline__ void gemm_phase(PG8_LAS unsigned char* lds, const Gemm g, const Sched& S, const Epi& E, const int wave_) {
;     ...
;             PG8_WAIT_V(8); PG8_WAIT_L(0); PG8_BAR; PG8_MMA(1, 0, At, B0); PG8_MMA(1, 1, At, B1); PG8_BAR; PG8_SCHED;
;             PG8_LDB(B0, 1, 0); PG8_LDB(B1, 1, 1); PG8_SCHED; PG8_LDA(At, 1, 0); PG8_STAGE(PG8_SA(0, 1), a2 + hstep, voffA);
;             PG8_WAIT_V(8); PG8_WAIT_L(0); PG8_BAR; PG8_MMA(0, 0, At, B0); PG8_MMA(0, 1, At, B1); PG8_BAR; PG8_SCHED;
	v_mfma_f32_16x16x32_bf16 v[60:63], v[146:149], v[188:191], v[60:63]
	v_mfma_f32_16x16x32_bf16 v[56:59], v[158:161], v[188:191], v[56:59]
	v_mfma_f32_16x16x32_bf16 v[44:47], v[146:149], v[200:203], v[44:47]
	v_mfma_f32_16x16x32_bf16 v[40:43], v[158:161], v[200:203], v[40:43]
	v_mfma_f32_16x16x32_bf16 v[28:31], v[146:149], v[208:211], v[28:31]
	v_mfma_f32_16x16x32_bf16 v[24:27], v[158:161], v[208:211], v[24:27]
	v_mfma_f32_16x16x32_bf16 v[12:15], v[146:149], v[216:219], v[12:15]
	v_mfma_f32_16x16x32_bf16 v[8:11], v[158:161], v[216:219], v[8:11]
	v_mfma_f32_16x16x32_bf16 v[60:63], v[154:157], v[196:199], v[60:63]
	v_mfma_f32_16x16x32_bf16 v[56:59], v[168:171], v[196:199], v[56:59]
	v_mfma_f32_16x16x32_bf16 v[44:47], v[154:157], v[204:207], v[44:47]
	v_mfma_f32_16x16x32_bf16 v[40:43], v[168:171], v[204:207], v[40:43]
	v_mfma_f32_16x16x32_bf16 v[28:31], v[154:157], v[212:215], v[28:31]
	v_mfma_f32_16x16x32_bf16 v[24:27], v[168:171], v[212:215], v[24:27]
	v_mfma_f32_16x16x32_bf16 v[12:15], v[154:157], v[220:223], v[12:15]
	v_mfma_f32_16x16x32_bf16 v[8:11], v[168:171], v[220:223], v[8:11]
	s_setprio 0
	s_setprio 1
	v_mfma_f32_16x16x32_bf16 v[52:55], v[172:175], v[188:191], v[52:55]
	v_mfma_f32_16x16x32_bf16 v[48:51], v[180:183], v[188:191], v[48:51]
	v_mfma_f32_16x16x32_bf16 v[36:39], v[172:175], v[200:203], v[36:39]
	v_mfma_f32_16x16x32_bf16 v[32:35], v[180:183], v[200:203], v[32:35]
	v_mfma_f32_16x16x32_bf16 v[20:23], v[172:175], v[208:211], v[20:23]
	v_mfma_f32_16x16x32_bf16 v[16:19], v[180:183], v[208:211], v[16:19]
	v_mfma_f32_16x16x32_bf16 v[4:7], v[172:175], v[216:219], v[4:7]
	v_mfma_f32_16x16x32_bf16 v[0:3], v[180:183], v[216:219], v[0:3]
	v_mfma_f32_16x16x32_bf16 v[52:55], v[176:179], v[196:199], v[52:55]
	v_mfma_f32_16x16x32_bf16 v[48:51], v[184:187], v[196:199], v[48:51]
	v_mfma_f32_16x16x32_bf16 v[36:39], v[176:179], v[204:207], v[36:39]
	v_mfma_f32_16x16x32_bf16 v[32:35], v[184:187], v[204:207], v[32:35]
	v_mfma_f32_16x16x32_bf16 v[20:23], v[176:179], v[212:215], v[20:23]
	v_mfma_f32_16x16x32_bf16 v[16:19], v[184:187], v[212:215], v[16:19]
	v_mfma_f32_16x16x32_bf16 v[4:7], v[176:179], v[220:223], v[4:7]
	v_mfma_f32_16x16x32_bf16 v[0:3], v[184:187], v[220:223], v[0:3]
	s_barrier
	s_setprio 0
	s_add_i32 s64, 0, 0x18000
	v_add_u32_e32 v136, s64, v162
	s_add_i32 s65, 0, 0x1c000
	ds_read_b128 v[146:149], v136
	ds_read_b128 v[154:157], v136 offset:1024
	ds_read_b128 v[158:161], v136 offset:2048
	ds_read_b128 v[168:171], v136 offset:3072
	v_add_u32_e32 v136, s65, v162
	ds_read_b128 v[172:175], v136
	ds_read_b128 v[176:179], v136 offset:1024
	ds_read_b128 v[180:183], v136 offset:2048
	ds_read_b128 v[184:187], v136 offset:3072
	s_add_u32 s42, s42, 0x80000
	s_addc_u32 s43, s43, 0
	s_mov_b32 m0, s47
	v_lshl_add_u64 v[228:229], s[42:43], 0, v[128:129]
	ds_read_b128 v[188:191], v166 offset:32768
	ds_read_b128 v[196:199], v166 offset:33792
	ds_read_b128 v[200:203], v166 offset:34816
	ds_read_b128 v[204:207], v166 offset:35840
	ds_read_b128 v[208:211], v166 offset:36864
	ds_read_b128 v[212:215], v166 offset:37888
	ds_read_b128 v[216:219], v166 offset:38912
	ds_read_b128 v[220:223], v166 offset:39936
	global_load_lds_dwordx4 v[228:229], off
	v_lshl_add_u64 v[228:229], s[42:43], 0, v[132:133]
	s_mov_b32 m0, s48
	s_nop 0
	global_load_lds_dwordx4 v[228:229], off
	s_waitcnt vmcnt(8)
	s_waitcnt lgkmcnt(0)
	s_setprio 1
	s_barrier
	v_mfma_f32_16x16x32_bf16 v[124:127], v[146:149], v[188:191], v[124:127]
	v_mfma_f32_16x16x32_bf16 v[120:123], v[158:161], v[188:191], v[120:123]
	v_mfma_f32_16x16x32_bf16 v[108:111], v[146:149], v[200:203], v[108:111]
	v_mfma_f32_16x16x32_bf16 v[104:107], v[158:161], v[200:203], v[104:107]
	v_mfma_f32_16x16x32_bf16 v[92:95], v[146:149], v[208:211], v[92:95]
	v_mfma_f32_16x16x32_bf16 v[88:91], v[158:161], v[208:211], v[88:91]
	v_mfma_f32_16x16x32_bf16 v[76:79], v[146:149], v[216:219], v[76:79]
	v_mfma_f32_16x16x32_bf16 v[72:75], v[158:161], v[216:219], v[72:75]
	v_mfma_f32_16x16x32_bf16 v[124:127], v[154:157], v[196:199], v[124:127]
	v_mfma_f32_16x16x32_bf16 v[120:123], v[168:171], v[196:199], v[120:123]
	v_mfma_f32_16x16x32_bf16 v[108:111], v[154:157], v[204:207], v[108:111]
	v_mfma_f32_16x16x32_bf16 v[104:107], v[168:171], v[204:207], v[104:107]
	v_mfma_f32_16x16x32_bf16 v[92:95], v[154:157], v[212:215], v[92:95]
	v_mfma_f32_16x16x32_bf16 v[88:91], v[168:171], v[212:215], v[88:91]
	v_mfma_f32_16x16x32_bf16 v[76:79], v[154:157], v[220:223], v[76:79]
	v_mfma_f32_16x16x32_bf16 v[72:75], v[168:171], v[220:223], v[72:75]
	s_setprio 0
	s_setprio 1
	v_mfma_f32_16x16x32_bf16 v[116:119], v[172:175], v[188:191], v[116:119]
	v_mfma_f32_16x16x32_bf16 v[112:115], v[180:183], v[188:191], v[112:115]
	v_mfma_f32_16x16x32_bf16 v[100:103], v[172:175], v[200:203], v[100:103]
	v_mfma_f32_16x16x32_bf16 v[96:99], v[180:183], v[200:203], v[96:99]
	v_mfma_f32_16x16x32_bf16 v[84:87], v[172:175], v[208:211], v[84:87]
	v_mfma_f32_16x16x32_bf16 v[80:83], v[180:183], v[208:211], v[80:83]
	v_mfma_f32_16x16x32_bf16 v[68:71], v[172:175], v[216:219], v[68:71]
	v_mfma_f32_16x16x32_bf16 v[64:67], v[180:183], v[216:219], v[64:67]
	v_mfma_f32_16x16x32_bf16 v[116:119], v[176:179], v[196:199], v[116:119]
	v_mfma_f32_16x16x32_bf16 v[112:115], v[184:187], v[196:199], v[112:115]
	v_mfma_f32_16x16x32_bf16 v[100:103], v[176:179], v[204:207], v[100:103]
	v_mfma_f32_16x16x32_bf16 v[96:99], v[184:187], v[204:207], v[96:99]
	v_mfma_f32_16x16x32_bf16 v[84:87], v[176:179], v[212:215], v[84:87]
	v_mfma_f32_16x16x32_bf16 v[80:83], v[184:187], v[212:215], v[80:83]
	v_mfma_f32_16x16x32_bf16 v[68:71], v[176:179], v[220:223], v[68:71]
	v_mfma_f32_16x16x32_bf16 v[64:67], v[184:187], v[220:223], v[64:67]
	s_barrier
; #define PG8_STAGE(bufoff, gbase, voff) do { _Pragma("unroll") for (int _i = 0; _i < 2; ++_i) \
;         __builtin_amdgcn_global_load_lds((const unsigned*)((const char*)(gbase) + (voff)[_i]), (PG8_LAS unsigned*)(lds + (bufoff) + ldsw + _i * 8192), 16, 0, 0); } while (0)
; #define PG8_LDA(dst, b, h) do { _Pragma("unroll") for (int m = 0; m < 4; ++m) _Pragma("unroll") for (int k = 0; k < 2; ++k) dst[m][k] = *(const PG8_LAS bf16x8*)(lds + PG8_SA(b, h) + aoff + m * 2048 + k * 1024); } while (0)
; #define PG8_MMA(ai, bj, At, Bt) do { __builtin_amdgcn_s_setprio(1); _Pragma("unroll") for (int m = 0; m < 4; ++m) _Pragma("unroll") for (int n = 0; n < 2; ++n) _Pragma("unroll") for (int k = 0; k < 2; ++k) \
;         acc[ai][bj][m][n] = __builtin_amdgcn_mfma_f32_16x16x32_bf16(Bt[n][k], At[m][k], acc[ai][bj][m][n], 0, 0, 0); __builtin_amdgcn_s_setprio(0); } while (0)
; #define PG8_WAIT_V(n) asm volatile("s_waitcnt vmcnt(" #n ")" ::: "memory")
; #define PG8_WAIT_L(n) asm volatile("s_waitcnt lgkmcnt(" #n ")" ::: "memory")
; #define PG8_BAR __builtin_amdgcn_s_barrier()
; #define PG8_SCHED __builtin_amdgcn_sched_barrier(0)
; template <class Epi, class Sched, bool ALIGN_EPI = false, bool SP2 = false>
; __device__ __forceinline__ void gemm_phase(PG8_LAS unsigned char* lds, const Gemm g, const Sched& S, const Epi& E, const int wave_) {
;     ...
;         for (int t = 0; t < nt; t += 2) {
;     ...
;             PG8_LDA(At, 1, 1); PG8_STAGE(PG8_SB(1, 0), b3, voffB); PG8_STAGE(PG8_SB(1, 1), b3 + hstep, voffB); PG8_STAGE(PG8_SA(1, 0), a3, voffA);
;             PG8_WAIT_V(8); PG8_WAIT_L(0); PG8_BAR; PG8_MMA(1, 0, At, B0); PG8_MMA(1, 1, At, B1); PG8_BAR; PG8_SCHED;
	s_setprio 0
	s_add_i32 s42, s64, s44
	v_lshl_add_u64 v[150:151], v[150:151], 0, s[18:19]
	s_mov_b32 m0, s42
	ds_read_b128 v[188:191], v166 offset:49152
	ds_read_b128 v[196:199], v166 offset:50176
	ds_read_b128 v[200:203], v166 offset:51200
	ds_read_b128 v[204:207], v166 offset:52224
	ds_read_b128 v[208:211], v166 offset:53248
	ds_read_b128 v[212:215], v166 offset:54272
	ds_read_b128 v[216:219], v166 offset:55296
	ds_read_b128 v[220:223], v166 offset:56320
	global_load_lds_dwordx4 v[150:151], off
	s_add_i32 m0, s42, 0x2000
	s_add_u32 s40, s40, 0x80080
	v_lshl_add_u64 v[150:151], v[192:193], 0, s[18:19]
	s_addc_u32 s41, s41, 0
	s_add_i32 s42, s65, s44
	global_load_lds_dwordx4 v[150:151], off
	v_lshl_add_u64 v[150:151], s[40:41], 0, v[130:131]
	s_mov_b32 m0, s42
	s_nop 0
	global_load_lds_dwordx4 v[150:151], off
	v_lshl_add_u64 v[150:151], s[40:41], 0, v[134:135]
	s_add_i32 m0, s42, 0x2000
	s_nop 0
	global_load_lds_dwordx4 v[150:151], off
	v_lshl_add_u64 v[150:151], v[224:225], 0, s[18:19]
	s_mov_b32 m0, s52
	s_nop 0
	global_load_lds_dwordx4 v[150:151], off
	v_lshl_add_u64 v[150:151], v[226:227], 0, s[18:19]
	s_mov_b32 m0, s53
	s_nop 0
	global_load_lds_dwordx4 v[150:151], off
	s_waitcnt vmcnt(8)
	s_waitcnt lgkmcnt(0)
	s_setprio 1
	s_barrier
	v_mfma_f32_16x16x32_bf16 v[60:63], v[146:149], v[188:191], v[60:63]
	v_mfma_f32_16x16x32_bf16 v[56:59], v[158:161], v[188:191], v[56:59]
	v_mfma_f32_16x16x32_bf16 v[44:47], v[146:149], v[200:203], v[44:47]
	v_mfma_f32_16x16x32_bf16 v[40:43], v[158:161], v[200:203], v[40:43]
	v_mfma_f32_16x16x32_bf16 v[28:31], v[146:149], v[208:211], v[28:31]
	v_mfma_f32_16x16x32_bf16 v[24:27], v[158:161], v[208:211], v[24:27]
	v_mfma_f32_16x16x32_bf16 v[12:15], v[146:149], v[216:219], v[12:15]
	v_mfma_f32_16x16x32_bf16 v[8:11], v[158:161], v[216:219], v[8:11]
	v_mfma_f32_16x16x32_bf16 v[60:63], v[154:157], v[196:199], v[60:63]
	v_mfma_f32_16x16x32_bf16 v[56:59], v[168:171], v[196:199], v[56:59]
	v_mfma_f32_16x16x32_bf16 v[44:47], v[154:157], v[204:207], v[44:47]
	v_mfma_f32_16x16x32_bf16 v[40:43], v[168:171], v[204:207], v[40:43]
	v_mfma_f32_16x16x32_bf16 v[28:31], v[154:157], v[212:215], v[28:31]
	v_mfma_f32_16x16x32_bf16 v[24:27], v[168:171], v[212:215], v[24:27]
	v_mfma_f32_16x16x32_bf16 v[12:15], v[154:157], v[220:223], v[12:15]
	v_mfma_f32_16x16x32_bf16 v[8:11], v[168:171], v[220:223], v[8:11]
	s_setprio 0
	s_setprio 1
	v_mfma_f32_16x16x32_bf16 v[52:55], v[172:175], v[188:191], v[52:55]
	v_mfma_f32_16x16x32_bf16 v[48:51], v[180:183], v[188:191], v[48:51]
	v_mfma_f32_16x16x32_bf16 v[36:39], v[172:175], v[200:203], v[36:39]
	v_mfma_f32_16x16x32_bf16 v[32:35], v[180:183], v[200:203], v[32:35]
	v_mfma_f32_16x16x32_bf16 v[20:23], v[172:175], v[208:211], v[20:23]
	v_mfma_f32_16x16x32_bf16 v[16:19], v[180:183], v[208:211], v[16:19]
	v_mfma_f32_16x16x32_bf16 v[4:7], v[172:175], v[216:219], v[4:7]
	v_mfma_f32_16x16x32_bf16 v[0:3], v[180:183], v[216:219], v[0:3]
	v_mfma_f32_16x16x32_bf16 v[52:55], v[176:179], v[196:199], v[52:55]
	v_mfma_f32_16x16x32_bf16 v[48:51], v[184:187], v[196:199], v[48:51]
	v_mfma_f32_16x16x32_bf16 v[36:39], v[176:179], v[204:207], v[36:39]
	v_mfma_f32_16x16x32_bf16 v[32:35], v[184:187], v[204:207], v[32:35]
	v_mfma_f32_16x16x32_bf16 v[20:23], v[176:179], v[212:215], v[20:23]
	v_mfma_f32_16x16x32_bf16 v[16:19], v[184:187], v[212:215], v[16:19]
	v_mfma_f32_16x16x32_bf16 v[4:7], v[176:179], v[220:223], v[4:7]
	v_mfma_f32_16x16x32_bf16 v[0:3], v[184:187], v[220:223], v[0:3]
	s_barrier
	s_setprio 0
	s_add_i32 s63, s63, 2
	s_add_u32 s36, s36, 0x100
	s_addc_u32 s37, s37, 0
	s_add_u32 s61, s61, 0x100
	s_addc_u32 s62, s62, 0
	s_cmp_gt_u32 s63, 29
	s_cbranch_scc0 .LBB0_495
	s_and_b64 vcc, exec, s[16:17]
	s_cbranch_vccz .LBB0_498
	s_barrier

; #define PG8_STAGE(bufoff, gbase, voff) do { _Pragma("unroll") for (int _i = 0; _i < 2; ++_i) \
;         __builtin_amdgcn_global_load_lds((const unsigned*)((const char*)(gbase) + (voff)[_i]), (PG8_LAS unsigned*)(lds + (bufoff) + ldsw + _i * 8192), 16, 0, 0); } while (0)
; #define PG8_LDA(dst, b, h) do { _Pragma("unroll") for (int m = 0; m < 4; ++m) _Pragma("unroll") for (int k = 0; k < 2; ++k) dst[m][k] = *(const PG8_LAS bf16x8*)(lds + PG8_SA(b, h) + aoff + m * 2048 + k * 1024); } while (0)
; #define PG8_LDB(dst, b, h) do { _Pragma("unroll") for (int n = 0; n < 2; ++n) _Pragma("unroll") for (int k = 0; k < 2; ++k) dst[n][k] = *(const PG8_LAS bf16x8*)(lds + PG8_SB(b, h) + boff + n * 2048 + k * 1024); } while (0)
; #define PG8_MMA(ai, bj, At, Bt) do { __builtin_amdgcn_s_setprio(1); _Pragma("unroll") for (int m = 0; m < 4; ++m) _Pragma("unroll") for (int n = 0; n < 2; ++n) _Pragma("unroll") for (int k = 0; k < 2; ++k) \
;         acc[ai][bj][m][n] = __builtin_amdgcn_mfma_f32_16x16x32_bf16(Bt[n][k], At[m][k], acc[ai][bj][m][n], 0, 0, 0); __builtin_amdgcn_s_setprio(0); } while (0)
; #define PG8_WAIT_V(n) asm volatile("s_waitcnt vmcnt(" #n ")" ::: "memory")
; #define PG8_WAIT_L(n) asm volatile("s_waitcnt lgkmcnt(" #n ")" ::: "memory")
; template <class Epi, class Sched, bool ALIGN_EPI = false, bool SP2 = false>
; __device__ __forceinline__ void gemm_phase(PG8_LAS unsigned char* lds, const Gemm g, const Sched& S, const Epi& E, const int wave_) {
;     ...
;             const bool last = (t == nt - 2);
;             const char* a1 = cA + (size_t)(t + 1) * kstep;
;             const char* a2 = last ? nA : cA + (size_t)(t + 2) * kstep; const char* b2 = last ? nB : cB + (size_t)(t + 2) * kstep;
;             const char* a3 = a2 + kstep; const char* b3 = b2 + kstep;
;             if (last && has_next) S.a_ready(nxt);
;             if constexpr (SP2) {
;             PG8_LDB(B0, 0, 0); PG8_LDB(B1, 0, 1); PG8_SCHED; PG8_LDA(At, 0, 0); PG8_STAGE(PG8_SA(1, 1), a1 + hstep, voffA);
;             PG8_WAIT_V(8); PG8_WAIT_L(0); PG8_BAR; PG8_MMA(0, 0, At, B0); PG8_MMA(0, 1, At, B1); PG8_BAR; PG8_SCHED;
;             PG8_LDA(At, 0, 1); PG8_STAGE(PG8_SB(0, 0), b2, voffB); PG8_STAGE(PG8_SB(0, 1), b2 + hstep, voffB); PG8_STAGE(PG8_SA(0, 0), a2, voffA);
;             PG8_WAIT_V(8); PG8_WAIT_L(0); PG8_BAR; PG8_MMA(1, 0, At, B0); PG8_MMA(1, 1, At, B1); PG8_BAR; PG8_SCHED;
.LBB0_700:
	ds_read_b128 v[128:131], v187
	ds_read_b128 v[132:135], v187 offset:1024
	ds_read_b128 v[136:139], v187 offset:2048
	ds_read_b128 v[140:143], v187 offset:3072
	ds_read_b128 v[160:163], v188
	ds_read_b128 v[164:167], v188 offset:1024
	ds_read_b128 v[168:171], v188 offset:2048
	ds_read_b128 v[172:175], v188 offset:3072
	s_add_u32 s36, s34, 0xfff80080
	s_addc_u32 s37, s35, -1
	s_cmp_eq_u32 s58, 28
	s_cselect_b32 s41, s23, s37
	s_cselect_b32 s40, s29, s36
	s_cselect_b32 s37, s21, s57
	s_cselect_b32 s36, s31, s56
	v_lshl_add_u64 v[180:181], s[34:35], 0, v[152:153]
	s_add_i32 m0, s42, 0xc000
	ds_read_b128 v[176:179], v189
	ds_read_b128 v[196:199], v189 offset:1024
	ds_read_b128 v[200:203], v189 offset:2048
	ds_read_b128 v[204:207], v189 offset:3072
	ds_read_b128 v[208:211], v189 offset:4096
	ds_read_b128 v[212:215], v189 offset:5120
	ds_read_b128 v[216:219], v189 offset:6144
	ds_read_b128 v[220:223], v189 offset:7168
	global_load_lds_dwordx4 v[180:181], off
	v_lshl_add_u64 v[180:181], s[34:35], 0, v[154:155]
	s_add_i32 m0, s42, 0xe000
	s_nop 0
	global_load_lds_dwordx4 v[180:181], off
	s_waitcnt vmcnt(8)
	s_waitcnt lgkmcnt(0)
	s_setprio 1
	s_barrier
	v_mfma_f32_16x16x32_bf16 v[40:43], v[128:131], v[176:179], v[40:43]
	v_mfma_f32_16x16x32_bf16 v[36:39], v[136:139], v[176:179], v[36:39]
	v_mfma_f32_16x16x32_bf16 v[68:71], v[128:131], v[200:203], v[68:71]
	v_mfma_f32_16x16x32_bf16 v[64:67], v[136:139], v[200:203], v[64:67]
	v_mfma_f32_16x16x32_bf16 v[100:103], v[128:131], v[208:211], v[100:103]
	v_mfma_f32_16x16x32_bf16 v[96:99], v[136:139], v[208:211], v[96:99]
	v_mfma_f32_16x16x32_bf16 v[124:127], v[128:131], v[216:219], v[124:127]
	v_mfma_f32_16x16x32_bf16 v[120:123], v[136:139], v[216:219], v[120:123]
	v_mfma_f32_16x16x32_bf16 v[40:43], v[132:135], v[196:199], v[40:43]
	v_mfma_f32_16x16x32_bf16 v[36:39], v[140:143], v[196:199], v[36:39]
	v_mfma_f32_16x16x32_bf16 v[68:71], v[132:135], v[204:207], v[68:71]
	v_mfma_f32_16x16x32_bf16 v[64:67], v[140:143], v[204:207], v[64:67]
	v_mfma_f32_16x16x32_bf16 v[100:103], v[132:135], v[212:215], v[100:103]
	v_mfma_f32_16x16x32_bf16 v[96:99], v[140:143], v[212:215], v[96:99]
	v_mfma_f32_16x16x32_bf16 v[124:127], v[132:135], v[220:223], v[124:127]
	v_mfma_f32_16x16x32_bf16 v[120:123], v[140:143], v[220:223], v[120:123]
	s_setprio 0
	s_setprio 1
	v_mfma_f32_16x16x32_bf16 v[44:47], v[160:163], v[176:179], v[44:47]
	v_mfma_f32_16x16x32_bf16 v[52:55], v[168:171], v[176:179], v[52:55]
	v_mfma_f32_16x16x32_bf16 v[72:75], v[160:163], v[200:203], v[72:75]
	v_mfma_f32_16x16x32_bf16 v[76:79], v[168:171], v[200:203], v[76:79]
	v_mfma_f32_16x16x32_bf16 v[104:107], v[160:163], v[208:211], v[104:107]
	v_mfma_f32_16x16x32_bf16 v[108:111], v[168:171], v[208:211], v[108:111]
	v_mfma_f32_16x16x32_bf16 v[116:119], v[160:163], v[216:219], v[116:119]
	v_mfma_f32_16x16x32_bf16 v[112:115], v[168:171], v[216:219], v[112:115]
	v_mfma_f32_16x16x32_bf16 v[44:47], v[164:167], v[196:199], v[44:47]
	v_mfma_f32_16x16x32_bf16 v[52:55], v[172:175], v[196:199], v[52:55]
	v_mfma_f32_16x16x32_bf16 v[72:75], v[164:167], v[204:207], v[72:75]
	v_mfma_f32_16x16x32_bf16 v[76:79], v[172:175], v[204:207], v[76:79]
	v_mfma_f32_16x16x32_bf16 v[104:107], v[164:167], v[212:215], v[104:107]
	v_mfma_f32_16x16x32_bf16 v[108:111], v[172:175], v[212:215], v[108:111]
	v_mfma_f32_16x16x32_bf16 v[116:119], v[164:167], v[220:223], v[116:119]
	v_mfma_f32_16x16x32_bf16 v[112:115], v[172:175], v[220:223], v[112:115]
	s_barrier
	s_setprio 0
	s_add_i32 s59, s54, s2
	v_lshl_add_u64 v[180:181], s[36:37], 0, v[146:147]
	s_mov_b32 m0, s59
	ds_read_b128 v[176:179], v189 offset:16384
	ds_read_b128 v[196:199], v189 offset:17408
	ds_read_b128 v[200:203], v189 offset:18432
	ds_read_b128 v[204:207], v189 offset:19456
	ds_read_b128 v[208:211], v189 offset:20480
	ds_read_b128 v[212:215], v189 offset:21504
	ds_read_b128 v[216:219], v189 offset:22528
	ds_read_b128 v[220:223], v189 offset:23552
	global_load_lds_dwordx4 v[180:181], off
	s_add_i32 m0, s59, 0x2000
	s_add_u32 s60, s36, 0x80000
	v_lshl_add_u64 v[192:193], s[36:37], 0, v[150:151]
	s_addc_u32 s61, s37, 0
	s_add_i32 s59, s55, s2
	global_load_lds_dwordx4 v[192:193], off
	v_lshl_add_u64 v[224:225], s[60:61], 0, v[146:147]
	s_mov_b32 m0, s59
	v_lshl_add_u64 v[226:227], s[40:41], 0, v[148:149]
	global_load_lds_dwordx4 v[224:225], off
	v_lshl_add_u64 v[224:225], s[60:61], 0, v[150:151]
	s_add_i32 m0, s59, 0x2000
	s_nop 0
	global_load_lds_dwordx4 v[224:225], off
	v_lshl_add_u64 v[224:225], s[40:41], 0, v[144:145]
	s_mov_b32 m0, s42
	s_nop 0
	global_load_lds_dwordx4 v[224:225], off
	s_mov_b32 m0, s43
	s_nop 0
	global_load_lds_dwordx4 v[226:227], off
	s_waitcnt vmcnt(8)
	s_waitcnt lgkmcnt(0)
	s_setprio 1
	s_barrier
; #define PG8_STAGE(bufoff, gbase, voff) do { _Pragma("unroll") for (int _i = 0; _i < 2; ++_i) \
;         __builtin_amdgcn_global_load_lds((const unsigned*)((const char*)(gbase) + (voff)[_i]), (PG8_LAS unsigned*)(lds + (bufoff) + ldsw + _i * 8192), 16, 0, 0); } while (0)
; #define PG8_LDA(dst, b, h) do { _Pragma("unroll") for (int m = 0; m < 4; ++m) _Pragma("unroll") for (int k = 0; k < 2; ++k) dst[m][k] = *(const PG8_LAS bf16x8*)(lds + PG8_SA(b, h) + aoff + m * 2048 + k * 1024); } while (0)
; #define PG8_LDB(dst, b, h) do { _Pragma("unroll") for (int n = 0; n < 2; ++n) _Pragma("unroll") for (int k = 0; k < 2; ++k) dst[n][k] = *(const PG8_LAS bf16x8*)(lds + PG8_SB(b, h) + boff + n * 2048 + k * 1024); } while (0)
; #define PG8_MMA(ai, bj, At, Bt) do { __builtin_amdgcn_s_setprio(1); _Pragma("unroll") for (int m = 0; m < 4; ++m) _Pragma("unroll") for (int n = 0; n < 2; ++n) _Pragma("unroll") for (int k = 0; k < 2; ++k) \
;         acc[ai][bj][m][n] = __builtin_amdgcn_mfma_f32_16x16x32_bf16(Bt[n][k], At[m][k], acc[ai][bj][m][n], 0, 0, 0); __builtin_amdgcn_s_setprio(0); } while (0)
; #define PG8_WAIT_V(n) asm volatile("s_waitcnt vmcnt(" #n ")" ::: "memory")
; #define PG8_WAIT_L(n) asm volatile("s_waitcnt lgkmcnt(" #n ")" ::: "memory")
; #define PG8_BAR __builtin_amdgcn_s_barrier()
; #define PG8_SCHED __builtin_amdgcn_sched_barrier(0)
; template <class Epi, class Sched, bool ALIGN_EPI = false, bool SP2 = false>
; __device__ __forceinline__ void gemm_phase(PG8_LAS unsigned char* lds, const Gemm g, const Sched& S, const Epi& E, const int wave_) {
;     ...
;             PG8_WAIT_V(8); PG8_WAIT_L(0); PG8_BAR; PG8_MMA(1, 0, At, B0); PG8_MMA(1, 1, At, B1); PG8_BAR; PG8_SCHED;
;             PG8_LDB(B0, 1, 0); PG8_LDB(B1, 1, 1); PG8_SCHED; PG8_LDA(At, 1, 0); PG8_STAGE(PG8_SA(0, 1), a2 + hstep, voffA);
;             PG8_WAIT_V(8); PG8_WAIT_L(0); PG8_BAR; PG8_MMA(0, 0, At, B0); PG8_MMA(0, 1, At, B1); PG8_BAR; PG8_SCHED;
	v_mfma_f32_16x16x32_bf16 v[92:95], v[128:131], v[176:179], v[92:95]
	v_mfma_f32_16x16x32_bf16 v[88:91], v[136:139], v[176:179], v[88:91]
	v_mfma_f32_16x16x32_bf16 v[60:63], v[128:131], v[200:203], v[60:63]
	v_mfma_f32_16x16x32_bf16 v[56:59], v[136:139], v[200:203], v[56:59]
	v_mfma_f32_16x16x32_bf16 v[28:31], v[128:131], v[208:211], v[28:31]
	v_mfma_f32_16x16x32_bf16 v[24:27], v[136:139], v[208:211], v[24:27]
	v_mfma_f32_16x16x32_bf16 v[12:15], v[128:131], v[216:219], v[12:15]
	v_mfma_f32_16x16x32_bf16 v[8:11], v[136:139], v[216:219], v[8:11]
	v_mfma_f32_16x16x32_bf16 v[92:95], v[132:135], v[196:199], v[92:95]
	v_mfma_f32_16x16x32_bf16 v[88:91], v[140:143], v[196:199], v[88:91]
	v_mfma_f32_16x16x32_bf16 v[60:63], v[132:135], v[204:207], v[60:63]
	v_mfma_f32_16x16x32_bf16 v[56:59], v[140:143], v[204:207], v[56:59]
	v_mfma_f32_16x16x32_bf16 v[28:31], v[132:135], v[212:215], v[28:31]
	v_mfma_f32_16x16x32_bf16 v[24:27], v[140:143], v[212:215], v[24:27]
	v_mfma_f32_16x16x32_bf16 v[12:15], v[132:135], v[220:223], v[12:15]
	v_mfma_f32_16x16x32_bf16 v[8:11], v[140:143], v[220:223], v[8:11]
	s_setprio 0
	s_setprio 1
	v_mfma_f32_16x16x32_bf16 v[84:87], v[160:163], v[176:179], v[84:87]
	v_mfma_f32_16x16x32_bf16 v[80:83], v[168:171], v[176:179], v[80:83]
	v_mfma_f32_16x16x32_bf16 v[48:51], v[160:163], v[200:203], v[48:51]
	v_mfma_f32_16x16x32_bf16 v[32:35], v[168:171], v[200:203], v[32:35]
	v_mfma_f32_16x16x32_bf16 v[20:23], v[160:163], v[208:211], v[20:23]
	v_mfma_f32_16x16x32_bf16 v[16:19], v[168:171], v[208:211], v[16:19]
	v_mfma_f32_16x16x32_bf16 v[4:7], v[160:163], v[216:219], v[4:7]
	v_mfma_f32_16x16x32_bf16 v[0:3], v[168:171], v[216:219], v[0:3]
	v_mfma_f32_16x16x32_bf16 v[84:87], v[164:167], v[196:199], v[84:87]
	v_mfma_f32_16x16x32_bf16 v[80:83], v[172:175], v[196:199], v[80:83]
	v_mfma_f32_16x16x32_bf16 v[48:51], v[164:167], v[204:207], v[48:51]
	v_mfma_f32_16x16x32_bf16 v[32:35], v[172:175], v[204:207], v[32:35]
	v_mfma_f32_16x16x32_bf16 v[20:23], v[164:167], v[212:215], v[20:23]
	v_mfma_f32_16x16x32_bf16 v[16:19], v[172:175], v[212:215], v[16:19]
	v_mfma_f32_16x16x32_bf16 v[4:7], v[164:167], v[220:223], v[4:7]
	v_mfma_f32_16x16x32_bf16 v[0:3], v[172:175], v[220:223], v[0:3]
	s_barrier
	s_setprio 0
	s_add_i32 s59, 0, 0x18000
	s_add_i32 s60, 0, 0x1c000
	v_add_u32_e32 v140, s59, v183
	v_add_u32_e32 v172, s60, v183
	ds_read_b128 v[128:131], v140
	ds_read_b128 v[132:135], v140 offset:1024
	ds_read_b128 v[136:139], v140 offset:2048
	ds_read_b128 v[140:143], v140 offset:3072
	ds_read_b128 v[160:163], v172
	ds_read_b128 v[164:167], v172 offset:1024
	ds_read_b128 v[168:171], v172 offset:2048
	ds_read_b128 v[172:175], v172 offset:3072
	s_add_u32 s40, s40, 0x80000
	s_addc_u32 s41, s41, 0
	s_mov_b32 m0, s44
	v_lshl_add_u64 v[228:229], s[40:41], 0, v[144:145]
	ds_read_b128 v[176:179], v189 offset:32768
	ds_read_b128 v[196:199], v189 offset:33792
	ds_read_b128 v[200:203], v189 offset:34816
	ds_read_b128 v[204:207], v189 offset:35840
	ds_read_b128 v[208:211], v189 offset:36864
	ds_read_b128 v[212:215], v189 offset:37888
	ds_read_b128 v[216:219], v189 offset:38912
	ds_read_b128 v[220:223], v189 offset:39936
	global_load_lds_dwordx4 v[228:229], off
	v_lshl_add_u64 v[228:229], s[40:41], 0, v[148:149]
	s_mov_b32 m0, s45
	s_nop 0
	global_load_lds_dwordx4 v[228:229], off
	s_waitcnt vmcnt(8)
	s_waitcnt lgkmcnt(0)
	s_setprio 1
	s_barrier
	v_mfma_f32_16x16x32_bf16 v[40:43], v[128:131], v[176:179], v[40:43]
	v_mfma_f32_16x16x32_bf16 v[36:39], v[136:139], v[176:179], v[36:39]
	v_mfma_f32_16x16x32_bf16 v[68:71], v[128:131], v[200:203], v[68:71]
	v_mfma_f32_16x16x32_bf16 v[64:67], v[136:139], v[200:203], v[64:67]
	v_mfma_f32_16x16x32_bf16 v[100:103], v[128:131], v[208:211], v[100:103]
	v_mfma_f32_16x16x32_bf16 v[96:99], v[136:139], v[208:211], v[96:99]
	v_mfma_f32_16x16x32_bf16 v[124:127], v[128:131], v[216:219], v[124:127]
	v_mfma_f32_16x16x32_bf16 v[120:123], v[136:139], v[216:219], v[120:123]
	v_mfma_f32_16x16x32_bf16 v[40:43], v[132:135], v[196:199], v[40:43]
	v_mfma_f32_16x16x32_bf16 v[36:39], v[140:143], v[196:199], v[36:39]
	v_mfma_f32_16x16x32_bf16 v[68:71], v[132:135], v[204:207], v[68:71]
	v_mfma_f32_16x16x32_bf16 v[64:67], v[140:143], v[204:207], v[64:67]
	v_mfma_f32_16x16x32_bf16 v[100:103], v[132:135], v[212:215], v[100:103]
	v_mfma_f32_16x16x32_bf16 v[96:99], v[140:143], v[212:215], v[96:99]
	v_mfma_f32_16x16x32_bf16 v[124:127], v[132:135], v[220:223], v[124:127]
	v_mfma_f32_16x16x32_bf16 v[120:123], v[140:143], v[220:223], v[120:123]
	s_setprio 0
	s_setprio 1
	v_mfma_f32_16x16x32_bf16 v[44:47], v[160:163], v[176:179], v[44:47]
	v_mfma_f32_16x16x32_bf16 v[52:55], v[168:171], v[176:179], v[52:55]
	v_mfma_f32_16x16x32_bf16 v[72:75], v[160:163], v[200:203], v[72:75]
	v_mfma_f32_16x16x32_bf16 v[76:79], v[168:171], v[200:203], v[76:79]
	v_mfma_f32_16x16x32_bf16 v[104:107], v[160:163], v[208:211], v[104:107]
	v_mfma_f32_16x16x32_bf16 v[108:111], v[168:171], v[208:211], v[108:111]
	v_mfma_f32_16x16x32_bf16 v[116:119], v[160:163], v[216:219], v[116:119]
	v_mfma_f32_16x16x32_bf16 v[112:115], v[168:171], v[216:219], v[112:115]
	v_mfma_f32_16x16x32_bf16 v[44:47], v[164:167], v[196:199], v[44:47]
	v_mfma_f32_16x16x32_bf16 v[52:55], v[172:175], v[196:199], v[52:55]
	v_mfma_f32_16x16x32_bf16 v[72:75], v[164:167], v[204:207], v[72:75]
	v_mfma_f32_16x16x32_bf16 v[76:79], v[172:175], v[204:207], v[76:79]
	v_mfma_f32_16x16x32_bf16 v[104:107], v[164:167], v[212:215], v[104:107]
	v_mfma_f32_16x16x32_bf16 v[108:111], v[172:175], v[212:215], v[108:111]
	v_mfma_f32_16x16x32_bf16 v[116:119], v[164:167], v[220:223], v[116:119]
	v_mfma_f32_16x16x32_bf16 v[112:115], v[172:175], v[220:223], v[112:115]
	s_barrier
; #define PG8_STAGE(bufoff, gbase, voff) do { _Pragma("unroll") for (int _i = 0; _i < 2; ++_i) \
;         __builtin_amdgcn_global_load_lds((const unsigned*)((const char*)(gbase) + (voff)[_i]), (PG8_LAS unsigned*)(lds + (bufoff) + ldsw + _i * 8192), 16, 0, 0); } while (0)
; #define PG8_LDA(dst, b, h) do { _Pragma("unroll") for (int m = 0; m < 4; ++m) _Pragma("unroll") for (int k = 0; k < 2; ++k) dst[m][k] = *(const PG8_LAS bf16x8*)(lds + PG8_SA(b, h) + aoff + m * 2048 + k * 1024); } while (0)
; #define PG8_MMA(ai, bj, At, Bt) do { __builtin_amdgcn_s_setprio(1); _Pragma("unroll") for (int m = 0; m < 4; ++m) _Pragma("unroll") for (int n = 0; n < 2; ++n) _Pragma("unroll") for (int k = 0; k < 2; ++k) \
;         acc[ai][bj][m][n] = __builtin_amdgcn_mfma_f32_16x16x32_bf16(Bt[n][k], At[m][k], acc[ai][bj][m][n], 0, 0, 0); __builtin_amdgcn_s_setprio(0); } while (0)
; #define PG8_WAIT_V(n) asm volatile("s_waitcnt vmcnt(" #n ")" ::: "memory")
; #define PG8_WAIT_L(n) asm volatile("s_waitcnt lgkmcnt(" #n ")" ::: "memory")
; #define PG8_BAR __builtin_amdgcn_s_barrier()
; #define PG8_SCHED __builtin_amdgcn_sched_barrier(0)
; template <class Epi, class Sched, bool ALIGN_EPI = false, bool SP2 = false>
; __device__ __forceinline__ void gemm_phase(PG8_LAS unsigned char* lds, const Gemm g, const Sched& S, const Epi& E, const int wave_) {
;     ...
;         for (int t = 0; t < nt; t += 2) {
;     ...
;             PG8_LDA(At, 1, 1); PG8_STAGE(PG8_SB(1, 0), b3, voffB); PG8_STAGE(PG8_SB(1, 1), b3 + hstep, voffB); PG8_STAGE(PG8_SA(1, 0), a3, voffA);
;             PG8_WAIT_V(8); PG8_WAIT_L(0); PG8_BAR; PG8_MMA(1, 0, At, B0); PG8_MMA(1, 1, At, B1); PG8_BAR; PG8_SCHED;
	s_setprio 0
	s_add_i32 s40, s59, s2
	v_lshl_add_u64 v[180:181], v[180:181], 0, s[18:19]
	s_mov_b32 m0, s40
	ds_read_b128 v[176:179], v189 offset:49152
	ds_read_b128 v[196:199], v189 offset:50176
	ds_read_b128 v[200:203], v189 offset:51200
	ds_read_b128 v[204:207], v189 offset:52224
	ds_read_b128 v[208:211], v189 offset:53248
	ds_read_b128 v[212:215], v189 offset:54272
	ds_read_b128 v[216:219], v189 offset:55296
	ds_read_b128 v[220:223], v189 offset:56320
	global_load_lds_dwordx4 v[180:181], off
	s_add_i32 m0, s40, 0x2000
	s_add_u32 s36, s36, 0x80080
	v_lshl_add_u64 v[180:181], v[192:193], 0, s[18:19]
	s_addc_u32 s37, s37, 0
	s_add_i32 s40, s60, s2
	global_load_lds_dwordx4 v[180:181], off
	v_lshl_add_u64 v[180:181], s[36:37], 0, v[146:147]
	s_mov_b32 m0, s40
	s_nop 0
	global_load_lds_dwordx4 v[180:181], off
	v_lshl_add_u64 v[180:181], s[36:37], 0, v[150:151]
	s_add_i32 m0, s40, 0x2000
	s_nop 0
	global_load_lds_dwordx4 v[180:181], off
	v_lshl_add_u64 v[180:181], v[224:225], 0, s[18:19]
	s_mov_b32 m0, s51
	s_nop 0
	global_load_lds_dwordx4 v[180:181], off
	v_lshl_add_u64 v[180:181], v[226:227], 0, s[18:19]
	s_mov_b32 m0, s52
	s_nop 0
	global_load_lds_dwordx4 v[180:181], off
	s_waitcnt vmcnt(8)
	s_waitcnt lgkmcnt(0)
	s_setprio 1
	s_barrier
	v_mfma_f32_16x16x32_bf16 v[92:95], v[128:131], v[176:179], v[92:95]
	v_mfma_f32_16x16x32_bf16 v[88:91], v[136:139], v[176:179], v[88:91]
	v_mfma_f32_16x16x32_bf16 v[60:63], v[128:131], v[200:203], v[60:63]
	v_mfma_f32_16x16x32_bf16 v[56:59], v[136:139], v[200:203], v[56:59]
	v_mfma_f32_16x16x32_bf16 v[28:31], v[128:131], v[208:211], v[28:31]
	v_mfma_f32_16x16x32_bf16 v[24:27], v[136:139], v[208:211], v[24:27]
	v_mfma_f32_16x16x32_bf16 v[12:15], v[128:131], v[216:219], v[12:15]
	v_mfma_f32_16x16x32_bf16 v[8:11], v[136:139], v[216:219], v[8:11]
	v_mfma_f32_16x16x32_bf16 v[92:95], v[132:135], v[196:199], v[92:95]
	v_mfma_f32_16x16x32_bf16 v[88:91], v[140:143], v[196:199], v[88:91]
	v_mfma_f32_16x16x32_bf16 v[60:63], v[132:135], v[204:207], v[60:63]
	v_mfma_f32_16x16x32_bf16 v[56:59], v[140:143], v[204:207], v[56:59]
	v_mfma_f32_16x16x32_bf16 v[28:31], v[132:135], v[212:215], v[28:31]
	v_mfma_f32_16x16x32_bf16 v[24:27], v[140:143], v[212:215], v[24:27]
	v_mfma_f32_16x16x32_bf16 v[12:15], v[132:135], v[220:223], v[12:15]
	v_mfma_f32_16x16x32_bf16 v[8:11], v[140:143], v[220:223], v[8:11]
	s_setprio 0
	s_setprio 1
	v_mfma_f32_16x16x32_bf16 v[84:87], v[160:163], v[176:179], v[84:87]
	v_mfma_f32_16x16x32_bf16 v[80:83], v[168:171], v[176:179], v[80:83]
	v_mfma_f32_16x16x32_bf16 v[48:51], v[160:163], v[200:203], v[48:51]
	v_mfma_f32_16x16x32_bf16 v[32:35], v[168:171], v[200:203], v[32:35]
	v_mfma_f32_16x16x32_bf16 v[20:23], v[160:163], v[208:211], v[20:23]
	v_mfma_f32_16x16x32_bf16 v[16:19], v[168:171], v[208:211], v[16:19]
	v_mfma_f32_16x16x32_bf16 v[4:7], v[160:163], v[216:219], v[4:7]
	v_mfma_f32_16x16x32_bf16 v[0:3], v[168:171], v[216:219], v[0:3]
	v_mfma_f32_16x16x32_bf16 v[84:87], v[164:167], v[196:199], v[84:87]
	v_mfma_f32_16x16x32_bf16 v[80:83], v[172:175], v[196:199], v[80:83]
	v_mfma_f32_16x16x32_bf16 v[48:51], v[164:167], v[204:207], v[48:51]
	v_mfma_f32_16x16x32_bf16 v[32:35], v[172:175], v[204:207], v[32:35]
	v_mfma_f32_16x16x32_bf16 v[20:23], v[164:167], v[212:215], v[20:23]
	v_mfma_f32_16x16x32_bf16 v[16:19], v[172:175], v[212:215], v[16:19]
	v_mfma_f32_16x16x32_bf16 v[4:7], v[164:167], v[220:223], v[4:7]
	v_mfma_f32_16x16x32_bf16 v[0:3], v[172:175], v[220:223], v[0:3]
	s_barrier
	s_setprio 0
	s_add_i32 s58, s58, 2
	s_add_u32 s34, s34, 0x100
	s_addc_u32 s35, s35, 0
	s_add_u32 s56, s56, 0x100
	s_addc_u32 s57, s57, 0
	s_cmp_gt_u32 s58, 29
	s_cbranch_scc0 .LBB0_700
	s_and_b64 vcc, exec, s[14:15]
	s_cbranch_vccz .LBB0_703
	s_barrier
